# v36 + FFN-up G stores merged to dwordx4 (second measurement)
# speedup vs baseline: 1.0169x; 1.0081x over previous
.LBB0_1407:
	s_or_b64 exec, exec, s[18:19]
	v_pk_mul_f32 v[106:107], v[106:107], v[114:115]
	v_pk_mul_f32 v[104:105], v[104:105], v[116:117]
	v_pk_mul_f32 v[200:201], v[112:113], v[116:117]
	v_pk_mul_f32 v[112:113], v[110:111], v[114:115]
	v_pk_mul_f32 v[202:203], v[108:109], v[116:117]
	v_pk_mul_f32 v[116:117], v[106:107], s[26:27] op_sel_hi:[1,0]
	v_pk_mul_f32 v[204:205], v[98:99], s[26:27] op_sel_hi:[1,0]
	v_pk_mul_f32 v[98:99], v[162:163], v[194:195] op_sel_hi:[0,1]
	v_pk_mul_f32 v[102:103], v[102:103], v[114:115]
	v_pk_mul_f32 v[110:111], v[104:105], s[26:27] op_sel_hi:[1,0]
	v_pk_mul_f32 v[112:113], v[112:113], s[26:27] op_sel_hi:[1,0]
	v_pk_mul_f32 v[114:115], v[200:201], s[26:27] op_sel_hi:[1,0]
	v_pk_mul_f32 v[200:201], v[202:203], s[26:27] op_sel_hi:[1,0]
	v_pk_mul_f32 v[202:203], v[100:101], s[26:27] op_sel_hi:[1,0]
	v_pk_mul_f32 v[100:101], v[162:163], v[192:193] op_sel_hi:[0,1]
	v_pk_mul_f32 v[104:105], v[162:163], v[188:189] op_sel:[1,0]
	v_pk_fma_f32 v[188:189], v[98:99], v[116:117], v[204:205]
	v_pk_mul_f32 v[108:109], v[102:103], s[26:27] op_sel_hi:[1,0]
	v_pk_mul_f32 v[102:103], v[162:163], v[190:191] op_sel:[1,0]
	v_pk_fma_f32 v[106:107], v[100:101], v[200:201], v[202:203]
	v_pk_fma_f32 v[188:189], v[112:113], v[90:91], v[188:189]
	v_pk_fma_f32 v[106:107], v[114:115], v[92:93], v[106:107]
	v_pk_fma_f32 v[94:95], v[108:109], v[94:95], v[188:189]
	v_pk_fma_f32 v[188:189], v[102:103], v[116:117], v[204:205]
	v_pk_fma_f32 v[96:97], v[110:111], v[96:97], v[106:107]
	v_pk_fma_f32 v[106:107], v[104:105], v[200:201], v[202:203]
	v_pk_fma_f32 v[188:189], v[98:99], v[112:113], v[188:189]
	v_pk_fma_f32 v[106:107], v[100:101], v[114:115], v[106:107]
	v_pk_fma_f32 v[90:91], v[108:109], v[90:91], v[188:189]
	v_pk_fma_f32 v[188:189], v[224:225], v[116:117], v[204:205]
	v_pk_fma_f32 v[92:93], v[110:111], v[92:93], v[106:107]
	v_pk_fma_f32 v[106:107], v[222:223], v[200:201], v[202:203]
	v_pk_fma_f32 v[188:189], v[102:103], v[112:113], v[188:189]
	v_pk_fma_f32 v[106:107], v[104:105], v[114:115], v[106:107]
	v_pk_fma_f32 v[190:191], v[98:99], v[108:109], v[188:189]
	v_pk_fma_f32 v[98:99], v[226:227], v[200:201], v[202:203]
	v_pk_fma_f32 v[100:101], v[100:101], v[110:111], v[106:107]
	v_pk_fma_f32 v[106:107], v[228:229], v[116:117], v[204:205]
	v_pk_fma_f32 v[98:99], v[222:223], v[114:115], v[98:99]
	v_pk_mul_f32 v[70:71], v[70:71], v[82:83]
	v_mov_b32_e32 v196, v165
	v_mov_b32_e32 v197, v165
	v_pk_fma_f32 v[106:107], v[224:225], v[112:113], v[106:107]
	v_pk_fma_f32 v[104:105], v[104:105], v[110:111], v[98:99]
	v_pk_mul_f32 v[80:81], v[80:81], v[84:85]
	v_pk_mul_f32 v[78:79], v[78:79], v[82:83]
	v_pk_mul_f32 v[98:99], v[76:77], v[84:85]
	v_pk_mul_f32 v[74:75], v[74:75], v[82:83]
	v_pk_mul_f32 v[72:73], v[72:73], v[84:85]
	v_pk_mul_f32 v[84:85], v[70:71], s[28:29] op_sel_hi:[1,0]
	v_mov_b32_e32 v70, v165
	v_mov_b32_e32 v71, v165
	v_mov_b32_e32 v198, v164
	v_mov_b32_e32 v199, v164
	v_pk_fma_f32 v[192:193], v[102:103], v[108:109], v[106:107]
	v_pk_mul_f32 v[76:77], v[78:79], s[28:29] op_sel_hi:[1,0]
	v_pk_mul_f32 v[78:79], v[80:81], s[28:29] op_sel_hi:[1,0]
	v_pk_mul_f32 v[80:81], v[74:75], s[28:29] op_sel_hi:[1,0]
	v_pk_mul_f32 v[82:83], v[98:99], s[28:29] op_sel_hi:[1,0]
	v_pk_mul_f32 v[98:99], v[72:73], s[28:29] op_sel_hi:[1,0]
	v_pk_mul_f32 v[102:103], v[68:69], s[28:29] op_sel_hi:[1,0]
	v_pk_mul_f32 v[106:107], v[66:67], s[28:29] op_sel_hi:[1,0]
	v_mov_b32_e32 v66, v164
	v_mov_b32_e32 v67, v164
	v_pk_mul_f32 v[70:71], v[70:71], v[210:211]
	v_pk_mul_f32 v[72:73], v[196:197], v[206:207]
	v_pk_mul_f32 v[74:75], v[162:163], v[220:221] op_sel_hi:[0,1]
	v_pk_mul_f32 v[194:195], v[162:163], v[218:219] op_sel_hi:[0,1]
	v_pk_mul_f32 v[66:67], v[66:67], v[212:213]
	v_pk_mul_f32 v[68:69], v[198:199], v[208:209]
	s_waitcnt lgkmcnt(0)
	v_mov_b32_dpp v86, v72 row_shr:1 row_mask:0xf bank_mask:0xf
	v_mov_b32_dpp v87, v73 row_shr:1 row_mask:0xf bank_mask:0xf
	v_mov_b32_dpp v88, v70 row_shr:1 row_mask:0xf bank_mask:0xf
	v_mov_b32_dpp v89, v71 row_shr:1 row_mask:0xf bank_mask:0xf
	v_pk_fma_f32 v[210:211], v[194:195], v[98:99], v[102:103]
	v_pk_fma_f32 v[212:213], v[74:75], v[84:85], v[106:107]
	v_mov_b32_dpp v62, v68 row_shr:1 row_mask:0xf bank_mask:0xf
	v_mov_b32_dpp v63, v69 row_shr:1 row_mask:0xf bank_mask:0xf
	v_mov_b32_dpp v64, v66 row_shr:1 row_mask:0xf bank_mask:0xf
	v_mov_b32_dpp v65, v67 row_shr:1 row_mask:0xf bank_mask:0xf
	v_pk_mul_f32 v[206:207], v[162:163], v[216:217] op_sel:[1,0]
	v_pk_mul_f32 v[208:209], v[162:163], v[214:215] op_sel:[1,0]
	v_pk_fma_f32 v[212:213], v[80:81], v[86:87], v[212:213]
	v_pk_fma_f32 v[210:211], v[82:83], v[88:89], v[210:211]
	v_pk_fma_f32 v[62:63], v[76:77], v[62:63], v[212:213]
	v_pk_fma_f32 v[64:65], v[78:79], v[64:65], v[210:211]
	v_pk_fma_f32 v[210:211], v[208:209], v[98:99], v[102:103]
	v_pk_fma_f32 v[212:213], v[206:207], v[84:85], v[106:107]
	v_pk_fma_f32 v[210:211], v[194:195], v[82:83], v[210:211]
	v_pk_fma_f32 v[212:213], v[74:75], v[80:81], v[212:213]
	v_pk_fma_f32 v[70:71], v[70:71], v[98:99], v[102:103]
	v_pk_fma_f32 v[72:73], v[72:73], v[84:85], v[106:107]
	v_pk_fma_f32 v[88:89], v[78:79], v[88:89], v[210:211]
	v_pk_fma_f32 v[86:87], v[76:77], v[86:87], v[212:213]
	v_pk_fma_f32 v[210:211], v[66:67], v[98:99], v[102:103]
	v_pk_fma_f32 v[212:213], v[68:69], v[84:85], v[106:107]
	v_pk_fma_f32 v[66:67], v[66:67], v[82:83], v[70:71]
	v_pk_fma_f32 v[68:69], v[68:69], v[80:81], v[72:73]
	v_exp_f32_e64 v70, -v94
	v_exp_f32_e64 v72, -v96
	v_exp_f32_e64 v73, -v97
	v_exp_f32_e64 v71, -v95
	s_lshl_b32 s9, s40, 8
	v_pk_mul_f32 v[62:63], v[94:95], v[62:63]
	v_pk_add_f32 v[72:73], v[72:73], 1.0 op_sel_hi:[1,0]
	v_pk_add_f32 v[70:71], v[70:71], 1.0 op_sel_hi:[1,0]
	v_rcp_f32_e32 v72, v72
	v_rcp_f32_e32 v70, v70
	v_rcp_f32_e32 v73, v73
	v_rcp_f32_e32 v71, v71
	v_pk_mul_f32 v[64:65], v[96:97], v[64:65]
	s_add_i32 s9, s9, s73
	v_pk_mul_f32 v[64:65], v[72:73], v[64:65]
	v_pk_mul_f32 v[62:63], v[70:71], v[62:63]
	v_exp_f32_e64 v72, -v90
	v_exp_f32_e64 v96, -v92
	v_exp_f32_e64 v97, -v93
	v_exp_f32_e64 v73, -v91
	v_add_u32_e32 v188, s9, v243
	v_pk_fma_f32 v[210:211], v[208:209], v[82:83], v[210:211]
	v_pk_fma_f32 v[212:213], v[206:207], v[80:81], v[212:213]
	v_cvt_pk_bf16_f32 v214, v62, v63
	v_cvt_pk_bf16_f32 v215, v64, v65
	v_mov_b64_e32 v[64:65], s[58:59]
	v_pk_fma_f32 v[194:195], v[194:195], v[78:79], v[210:211]
	v_pk_fma_f32 v[210:211], v[74:75], v[76:77], v[212:213]
	v_mad_i64_i32 v[70:71], s[18:19], v188, s17, v[64:65]
	v_lshlrev_b64 v[74:75], 1, v[186:187]
	v_lshl_add_u64 v[94:95], v[70:71], 0, v[74:75]
	v_pk_add_f32 v[62:63], v[96:97], 1.0 op_sel_hi:[1,0]
	v_pk_add_f32 v[70:71], v[72:73], 1.0 op_sel_hi:[1,0]
	v_rcp_f32_e32 v62, v62
	v_rcp_f32_e32 v70, v70
	v_rcp_f32_e32 v63, v63
	v_rcp_f32_e32 v71, v71
	v_pk_mul_f32 v[72:73], v[90:91], v[86:87]
	v_pk_mul_f32 v[86:87], v[92:93], v[88:89]
	v_pk_fma_f32 v[66:67], v[208:209], v[78:79], v[66:67]
	v_pk_mul_f32 v[62:63], v[62:63], v[86:87]
	v_pk_mul_f32 v[70:71], v[70:71], v[72:73]
	v_exp_f32_e64 v72, -v190
	v_exp_f32_e64 v86, -v100
	v_exp_f32_e64 v87, -v101
	v_exp_f32_e64 v73, -v191
	v_cvt_pk_bf16_f32 v218, v70, v71
	v_cvt_pk_bf16_f32 v219, v62, v63
	v_or_b32_e32 v62, 1, v188
	v_mad_i64_i32 v[62:63], s[18:19], v62, s17, v[64:65]
	v_lshl_add_u64 v[96:97], v[62:63], 0, v[74:75]
	v_pk_add_f32 v[62:63], v[86:87], 1.0 op_sel_hi:[1,0]
	v_pk_add_f32 v[70:71], v[72:73], 1.0 op_sel_hi:[1,0]
	v_rcp_f32_e32 v62, v62
	v_rcp_f32_e32 v70, v70
	v_rcp_f32_e32 v63, v63
	v_rcp_f32_e32 v71, v71
	v_pk_mul_f32 v[72:73], v[190:191], v[210:211]
	v_pk_mul_f32 v[86:87], v[100:101], v[194:195]
	v_pk_fma_f32 v[68:69], v[206:207], v[76:77], v[68:69]
	v_pk_mul_f32 v[62:63], v[86:87], v[62:63]
	v_pk_mul_f32 v[70:71], v[72:73], v[70:71]
	v_exp_f32_e64 v72, -v192
	v_exp_f32_e64 v86, -v104
	v_exp_f32_e64 v87, -v105
	v_exp_f32_e64 v73, -v193
	v_cvt_pk_bf16_f32 v222, v70, v71
	v_cvt_pk_bf16_f32 v223, v62, v63
	v_or_b32_e32 v62, 2, v188
	v_mad_i64_i32 v[62:63], s[18:19], v62, s17, v[64:65]
	v_lshl_add_u64 v[100:101], v[62:63], 0, v[74:75]
	v_pk_add_f32 v[62:63], v[86:87], 1.0 op_sel_hi:[1,0]
	v_pk_add_f32 v[70:71], v[72:73], 1.0 op_sel_hi:[1,0]
	v_rcp_f32_e32 v62, v62
	v_rcp_f32_e32 v70, v70
	v_rcp_f32_e32 v63, v63
	v_rcp_f32_e32 v71, v71
	v_pk_mul_f32 v[68:69], v[192:193], v[68:69]
	v_pk_mul_f32 v[66:67], v[104:105], v[66:67]
	v_lshl_add_u32 v186, v239, 5, v233
	v_pk_mul_f32 v[62:63], v[66:67], v[62:63]
	v_pk_mul_f32 v[66:67], v[68:69], v[70:71]
	v_mov_b32_e32 v70, 0
	v_cvt_pk_bf16_f32 v226, v66, v67
	v_cvt_pk_bf16_f32 v227, v62, v63
	v_or_b32_e32 v62, 3, v188
	v_mad_i64_i32 v[62:63], s[18:19], v62, s17, v[64:65]
	v_lshl_add_u64 v[104:105], v[62:63], 0, v[74:75]
	v_mov_b32_e32 v62, 0
	v_mov_b32_e32 v71, 0
	v_mov_b32_e32 v72, 0
	v_mov_b32_e32 v73, 0
	v_mov_b32_e32 v66, 0
	v_mov_b32_e32 v67, 0
	v_mov_b32_e32 v68, 0
	v_mov_b32_e32 v69, 0
	s_and_saveexec_b64 s[18:19], vcc
	s_cbranch_execz .LBB0_1409
	ds_read_b128 v[70:73], v186
	ds_read_b128 v[66:69], v186 offset:16

.LBB0_1411:
	s_or_b64 exec, exec, s[18:19]
	v_cvt_f32_i32_e32 v57, v57
	v_cvt_f32_i32_e32 v56, v56
	v_cvt_f32_i32_e32 v55, v55
	v_cvt_f32_i32_e32 v54, v54
	v_cvt_f32_i32_e32 v53, v53
	v_cvt_f32_i32_e32 v52, v52
	v_cvt_f32_i32_e32 v51, v51
	v_cvt_f32_i32_e32 v50, v50
	v_pk_mul_f32 v[56:57], v[130:131], v[56:57] op_sel_hi:[0,1]
	v_pk_fma_f32 v[190:191], v[56:57], v[200:201], v[202:203]
	v_pk_mul_f32 v[54:55], v[130:131], v[54:55] op_sel_hi:[0,1]
	v_pk_mul_f32 v[52:53], v[130:131], v[52:53] op_sel:[1,0]
	v_pk_fma_f32 v[190:191], v[114:115], v[68:69], v[190:191]
	v_pk_fma_f32 v[192:193], v[54:55], v[116:117], v[204:205]
	v_pk_fma_f32 v[72:73], v[110:111], v[72:73], v[190:191]
	v_pk_fma_f32 v[190:191], v[52:53], v[200:201], v[202:203]
	v_cvt_f32_i32_e32 v41, v41
	v_cvt_f32_i32_e32 v40, v40
	v_pk_mul_f32 v[50:51], v[130:131], v[50:51] op_sel:[1,0]
	v_pk_fma_f32 v[192:193], v[112:113], v[66:67], v[192:193]
	v_pk_fma_f32 v[190:191], v[56:57], v[114:115], v[190:191]
	v_pk_fma_f32 v[134:135], v[134:135], v[200:201], v[202:203]
	v_cvt_f32_i32_e32 v49, v49
	v_cvt_f32_i32_e32 v48, v48
	v_cvt_f32_i32_e32 v47, v47
	v_cvt_f32_i32_e32 v46, v46
	v_cvt_f32_i32_e32 v35, v35
	v_cvt_f32_i32_e32 v37, v37
	v_cvt_f32_i32_e32 v36, v36
	v_cvt_f32_i32_e32 v34, v34
	v_pk_fma_f32 v[70:71], v[108:109], v[70:71], v[192:193]
	v_pk_fma_f32 v[192:193], v[50:51], v[116:117], v[204:205]
	v_pk_fma_f32 v[68:69], v[110:111], v[68:69], v[190:191]
	v_pk_fma_f32 v[190:191], v[86:87], v[200:201], v[202:203]
	v_pk_fma_f32 v[86:87], v[86:87], v[114:115], v[134:135]
	v_cvt_f32_i32_e32 v39, v39
	v_cvt_f32_i32_e32 v38, v38
	v_pk_fma_f32 v[192:193], v[54:55], v[112:113], v[192:193]
	v_pk_fma_f32 v[190:191], v[52:53], v[114:115], v[190:191]
	v_pk_fma_f32 v[52:53], v[52:53], v[110:111], v[86:87]
	v_cvt_f32_i32_e32 v45, v45
	v_cvt_f32_i32_e32 v44, v44
	v_cvt_f32_i32_e32 v43, v43
	v_cvt_f32_i32_e32 v42, v42
	v_mov_b32_e32 v86, v132
	v_mov_b32_e32 v87, v132
	v_mov_b32_e32 v90, v133
	v_mov_b32_e32 v91, v133
	v_pk_fma_f32 v[66:67], v[108:109], v[66:67], v[192:193]
	v_pk_fma_f32 v[192:193], v[88:89], v[116:117], v[204:205]
	v_pk_fma_f32 v[116:117], v[136:137], v[116:117], v[204:205]
	v_pk_mul_f32 v[40:41], v[86:87], v[40:41]
	v_mov_b32_e32 v86, v133
	v_mov_b32_e32 v87, v133
	v_mov_b32_e32 v92, v132
	v_mov_b32_e32 v93, v132
	v_pk_fma_f32 v[88:89], v[88:89], v[112:113], v[116:117]
	v_pk_mul_f32 v[36:37], v[86:87], v[36:37]
	v_pk_mul_f32 v[34:35], v[90:91], v[34:35]
	v_pk_mul_f32 v[46:47], v[130:131], v[46:47] op_sel_hi:[0,1]
	v_pk_mul_f32 v[48:49], v[130:131], v[48:49] op_sel_hi:[0,1]
	v_pk_fma_f32 v[192:193], v[50:51], v[112:113], v[192:193]
	v_pk_fma_f32 v[50:51], v[50:51], v[108:109], v[88:89]
	v_pk_mul_f32 v[38:39], v[92:93], v[38:39]
	s_waitcnt lgkmcnt(0)
	v_mov_b32_dpp v58, v34 row_shr:1 row_mask:0xf bank_mask:0xf
	v_mov_b32_dpp v59, v35 row_shr:1 row_mask:0xf bank_mask:0xf
	v_mov_b32_dpp v60, v36 row_shr:1 row_mask:0xf bank_mask:0xf
	v_mov_b32_dpp v61, v37 row_shr:1 row_mask:0xf bank_mask:0xf
	v_pk_fma_f32 v[86:87], v[48:49], v[98:99], v[102:103]
	v_pk_fma_f32 v[88:89], v[46:47], v[84:85], v[106:107]
	v_mov_b32_dpp v62, v38 row_shr:1 row_mask:0xf bank_mask:0xf
	v_mov_b32_dpp v63, v39 row_shr:1 row_mask:0xf bank_mask:0xf
	v_mov_b32_dpp v64, v40 row_shr:1 row_mask:0xf bank_mask:0xf
	v_mov_b32_dpp v65, v41 row_shr:1 row_mask:0xf bank_mask:0xf
	v_pk_mul_f32 v[42:43], v[130:131], v[42:43] op_sel:[1,0]
	v_pk_mul_f32 v[44:45], v[130:131], v[44:45] op_sel:[1,0]
	v_pk_fma_f32 v[86:87], v[82:83], v[60:61], v[86:87]
	v_pk_fma_f32 v[88:89], v[80:81], v[58:59], v[88:89]
	v_pk_fma_f32 v[64:65], v[78:79], v[64:65], v[86:87]
	v_pk_fma_f32 v[62:63], v[76:77], v[62:63], v[88:89]
	v_pk_fma_f32 v[86:87], v[44:45], v[98:99], v[102:103]
	v_pk_fma_f32 v[88:89], v[42:43], v[84:85], v[106:107]
	v_pk_fma_f32 v[86:87], v[48:49], v[82:83], v[86:87]
	v_pk_fma_f32 v[88:89], v[46:47], v[80:81], v[88:89]
	v_pk_fma_f32 v[36:37], v[36:37], v[98:99], v[102:103]
	v_pk_fma_f32 v[34:35], v[34:35], v[84:85], v[106:107]
	v_pk_fma_f32 v[60:61], v[78:79], v[60:61], v[86:87]
	v_pk_fma_f32 v[58:59], v[76:77], v[58:59], v[88:89]
	v_pk_fma_f32 v[86:87], v[40:41], v[98:99], v[102:103]
	v_pk_fma_f32 v[88:89], v[38:39], v[84:85], v[106:107]
	v_pk_fma_f32 v[36:37], v[40:41], v[82:83], v[36:37]
	v_pk_fma_f32 v[34:35], v[38:39], v[80:81], v[34:35]
	v_exp_f32_e64 v38, -v70
	v_exp_f32_e64 v40, -v72
	v_exp_f32_e64 v41, -v73
	v_exp_f32_e64 v39, -v71
	v_pk_fma_f32 v[88:89], v[42:43], v[80:81], v[88:89]
	v_pk_fma_f32 v[86:87], v[44:45], v[82:83], v[86:87]
	v_pk_add_f32 v[40:41], v[40:41], 1.0 op_sel_hi:[1,0]
	v_pk_add_f32 v[38:39], v[38:39], 1.0 op_sel_hi:[1,0]
	v_rcp_f32_e32 v40, v40
	v_rcp_f32_e32 v38, v38
	v_rcp_f32_e32 v41, v41
	v_rcp_f32_e32 v39, v39
	v_pk_fma_f32 v[36:37], v[44:45], v[78:79], v[36:37]
	v_pk_fma_f32 v[34:35], v[42:43], v[76:77], v[34:35]
	v_pk_mul_f32 v[42:43], v[72:73], v[64:65]
	v_pk_mul_f32 v[44:45], v[70:71], v[62:63]
	v_pk_mul_f32 v[40:41], v[40:41], v[42:43]
	v_pk_mul_f32 v[38:39], v[38:39], v[44:45]
	v_exp_f32_e64 v44, -v66
	v_exp_f32_e64 v62, -v68
	v_exp_f32_e64 v63, -v69
	v_exp_f32_e64 v45, -v67
	v_pk_fma_f32 v[46:47], v[46:47], v[76:77], v[88:89]
	v_add_u32_e32 v76, 0x80, v188
	v_cvt_pk_bf16_f32 v242, v38, v39
	v_cvt_pk_bf16_f32 v243, v40, v41
	v_mov_b64_e32 v[40:41], s[58:59]
	v_mad_i64_i32 v[42:43], s[18:19], v76, s17, v[40:41]
	v_lshl_add_u64 v[98:99], v[42:43], 0, v[74:75]
	v_pk_add_f32 v[38:39], v[62:63], 1.0 op_sel_hi:[1,0]
	v_pk_add_f32 v[42:43], v[44:45], 1.0 op_sel_hi:[1,0]
	v_rcp_f32_e32 v38, v38
	v_rcp_f32_e32 v42, v42
	v_rcp_f32_e32 v39, v39
	v_rcp_f32_e32 v43, v43
	v_pk_fma_f32 v[56:57], v[56:57], v[110:111], v[190:191]
	v_pk_fma_f32 v[54:55], v[54:55], v[108:109], v[192:193]
	v_pk_mul_f32 v[44:45], v[68:69], v[60:61]
	v_pk_mul_f32 v[58:59], v[66:67], v[58:59]
	v_pk_mul_f32 v[38:39], v[38:39], v[44:45]
	v_pk_mul_f32 v[42:43], v[42:43], v[58:59]
	v_exp_f32_e64 v44, -v54
	v_exp_f32_e64 v58, -v56
	v_exp_f32_e64 v59, -v57
	v_exp_f32_e64 v45, -v55
	v_cvt_pk_bf16_f32 v246, v42, v43
	v_cvt_pk_bf16_f32 v247, v38, v39
	v_add_u32_e32 v38, 0x81, v188
	v_mad_i64_i32 v[38:39], s[18:19], v38, s17, v[40:41]
	v_lshl_add_u64 v[102:103], v[38:39], 0, v[74:75]
	v_pk_add_f32 v[38:39], v[58:59], 1.0 op_sel_hi:[1,0]
	v_pk_add_f32 v[42:43], v[44:45], 1.0 op_sel_hi:[1,0]
	v_rcp_f32_e32 v38, v38
	v_rcp_f32_e32 v42, v42
	v_rcp_f32_e32 v39, v39
	v_rcp_f32_e32 v43, v43
	v_pk_fma_f32 v[48:49], v[48:49], v[78:79], v[86:87]
	v_pk_mul_f32 v[44:45], v[54:55], v[46:47]
	v_pk_mul_f32 v[46:47], v[56:57], v[48:49]
	v_pk_mul_f32 v[42:43], v[44:45], v[42:43]
	v_pk_mul_f32 v[38:39], v[46:47], v[38:39]
	v_exp_f32_e64 v44, -v50
	v_exp_f32_e64 v46, -v52
	v_exp_f32_e64 v47, -v53
	v_exp_f32_e64 v45, -v51
	v_cvt_pk_bf16_f32 v250, v42, v43
	v_cvt_pk_bf16_f32 v251, v38, v39
	v_add_u32_e32 v38, 0x82, v188
	v_mad_i64_i32 v[38:39], s[18:19], v38, s17, v[40:41]
	v_lshl_add_u64 v[106:107], v[38:39], 0, v[74:75]
	v_pk_add_f32 v[38:39], v[46:47], 1.0 op_sel_hi:[1,0]
	v_pk_add_f32 v[42:43], v[44:45], 1.0 op_sel_hi:[1,0]
	v_rcp_f32_e32 v38, v38
	v_rcp_f32_e32 v42, v42
	v_rcp_f32_e32 v39, v39
	v_rcp_f32_e32 v43, v43
	v_pk_mul_f32 v[36:37], v[52:53], v[36:37]
	v_pk_mul_f32 v[34:35], v[50:51], v[34:35]
	v_pk_mul_f32 v[36:37], v[36:37], v[38:39]
	v_pk_mul_f32 v[34:35], v[34:35], v[42:43]
	v_mov_b32_e32 v66, 0
	v_cvt_pk_bf16_f32 v34, v34, v35
	v_cvt_pk_bf16_f32 v35, v36, v37
	v_add_u32_e32 v36, 0x83, v188
	v_mad_i64_i32 v[36:37], s[18:19], v36, s17, v[40:41]
	v_lshl_add_u64 v[108:109], v[36:37], 0, v[74:75]
	global_store_dwordx2 v[108:109], v[34:35], off
	ds_read_b128 v[74:77], v241 offset:16
	ds_read_b128 v[50:53], v241 offset:528
	ds_read_b128 v[82:85], v241 offset:1040
	ds_read_b128 v[46:49], v241 offset:1552
	ds_read_b128 v[78:81], v241 offset:2064
	ds_read_b128 v[42:45], v241 offset:2576
	ds_read_b128 v[70:73], v241 offset:3088
	ds_read_b128 v[38:41], v241 offset:3600
	ds_read_b128 v[86:89], v241 offset:4112
	ds_read_b128 v[54:57], v241 offset:4624
	v_mov_b32_e32 v34, 0
	v_mov_b32_e32 v67, 0
	v_mov_b32_e32 v68, 0
	v_mov_b32_e32 v69, 0
	v_mov_b32_e32 v62, 0
	v_mov_b32_e32 v63, 0
	v_mov_b32_e32 v64, 0
	v_mov_b32_e32 v65, 0
	s_and_saveexec_b64 s[18:19], s[6:7]
	s_cbranch_execz .LBB0_1413
	ds_read_b128 v[66:69], v240 offset:128
	ds_read_b128 v[62:65], v240 offset:144

.LBB0_1415:
	s_or_b64 exec, exec, s[18:19]
	v_pk_mul_f32 v[74:75], v[74:75], v[86:87]
	v_pk_mul_f32 v[82:83], v[82:83], v[86:87]
	v_pk_mul_f32 v[86:87], v[78:79], v[86:87]
	v_pk_mul_f32 v[136:137], v[76:77], v[88:89]
	v_pk_mul_f32 v[84:85], v[84:85], v[88:89]
	v_pk_mul_f32 v[88:89], v[80:81], v[88:89]
	v_pk_mul_f32 v[78:79], v[82:83], s[26:27] op_sel_hi:[1,0]
	v_pk_mul_f32 v[82:83], v[86:87], s[26:27] op_sel_hi:[1,0]
	v_mov_b32_e32 v86, v162
	v_mov_b32_e32 v87, v162
	v_mov_b32_e32 v128, v162
	v_mov_b32_e32 v129, v162
	v_pk_mul_f32 v[80:81], v[84:85], s[26:27] op_sel_hi:[1,0]
	v_pk_mul_f32 v[84:85], v[88:89], s[26:27] op_sel_hi:[1,0]
	v_pk_mul_f32 v[72:73], v[72:73], s[26:27] op_sel_hi:[1,0]
	v_pk_mul_f32 v[88:89], v[86:87], v[124:125]
	v_pk_mul_f32 v[70:71], v[70:71], s[26:27] op_sel_hi:[1,0]
	v_pk_mul_f32 v[120:121], v[128:129], v[120:121]
	v_mov_b32_e32 v162, v163
	v_pk_fma_f32 v[124:125], v[88:89], v[84:85], v[72:73]
	v_mov_b32_e32 v134, v163
	v_mov_b32_e32 v135, v163
	v_pk_mul_f32 v[76:77], v[74:75], s[26:27] op_sel_hi:[1,0]
	v_pk_mul_f32 v[74:75], v[136:137], s[26:27] op_sel_hi:[1,0]
	v_pk_mul_f32 v[122:123], v[162:163], v[122:123]
	v_pk_fma_f32 v[136:137], v[120:121], v[82:83], v[70:71]
	v_pk_fma_f32 v[124:125], v[80:81], v[64:65], v[124:125]
	v_pk_mul_f32 v[118:119], v[134:135], v[118:119]
	v_pk_fma_f32 v[136:137], v[78:79], v[62:63], v[136:137]
	v_pk_fma_f32 v[68:69], v[74:75], v[68:69], v[124:125]
	v_pk_fma_f32 v[124:125], v[122:123], v[84:85], v[72:73]
	v_pk_fma_f32 v[66:67], v[76:77], v[66:67], v[136:137]
	v_pk_fma_f32 v[136:137], v[118:119], v[82:83], v[70:71]
	v_pk_fma_f32 v[124:125], v[88:89], v[80:81], v[124:125]
	v_pk_fma_f32 v[136:137], v[120:121], v[78:79], v[136:137]
	v_pk_fma_f32 v[124:125], v[74:75], v[64:65], v[124:125]
	v_pk_fma_f32 v[64:65], v[114:115], v[82:83], v[70:71]
	v_pk_fma_f32 v[136:137], v[76:77], v[62:63], v[136:137]
	v_pk_fma_f32 v[62:63], v[112:113], v[84:85], v[72:73]
	v_pk_fma_f32 v[64:65], v[118:119], v[78:79], v[64:65]
	v_pk_fma_f32 v[62:63], v[122:123], v[80:81], v[62:63]
	v_pk_fma_f32 v[120:121], v[120:121], v[76:77], v[64:65]
	v_pk_fma_f32 v[64:65], v[126:127], v[82:83], v[70:71]
	v_pk_fma_f32 v[88:89], v[88:89], v[74:75], v[62:63]
	v_pk_fma_f32 v[62:63], v[116:117], v[84:85], v[72:73]
	v_pk_fma_f32 v[64:65], v[114:115], v[78:79], v[64:65]
	v_pk_fma_f32 v[62:63], v[112:113], v[80:81], v[62:63]
	v_pk_fma_f32 v[114:115], v[118:119], v[76:77], v[64:65]
	v_pk_mul_f32 v[50:51], v[50:51], v[54:55]
	v_pk_mul_f32 v[64:65], v[46:47], v[54:55]
	v_pk_mul_f32 v[44:45], v[44:45], v[56:57]
	v_pk_mul_f32 v[42:43], v[42:43], v[54:55]
	v_pk_fma_f32 v[112:113], v[122:123], v[74:75], v[62:63]
	v_pk_mul_f32 v[52:53], v[52:53], v[56:57]
	v_pk_mul_f32 v[62:63], v[48:49], v[56:57]
	v_pk_mul_f32 v[46:47], v[50:51], s[28:29] op_sel_hi:[1,0]
	v_pk_mul_f32 v[50:51], v[64:65], s[28:29] op_sel_hi:[1,0]
	v_pk_mul_f32 v[54:55], v[42:43], s[28:29] op_sel_hi:[1,0]
	v_pk_mul_f32 v[56:57], v[44:45], s[28:29] op_sel_hi:[1,0]
	v_pk_mul_f32 v[64:65], v[38:39], s[28:29] op_sel_hi:[1,0]
	v_pk_mul_f32 v[38:39], v[110:111], v[176:177]
	v_pk_mul_f32 v[44:45], v[196:197], v[170:171]
	v_pk_mul_f32 v[110:111], v[128:129], v[180:181]
	v_pk_mul_f32 v[48:49], v[52:53], s[28:29] op_sel_hi:[1,0]
	v_pk_mul_f32 v[52:53], v[62:63], s[28:29] op_sel_hi:[1,0]
	v_pk_mul_f32 v[62:63], v[40:41], s[28:29] op_sel_hi:[1,0]
	v_pk_mul_f32 v[40:41], v[198:199], v[172:173]
	v_pk_mul_f32 v[42:43], v[164:165], v[174:175]
	s_waitcnt lgkmcnt(0)
	v_mov_b32_dpp v58, v44 row_shr:1 row_mask:0xf bank_mask:0xf
	v_mov_b32_dpp v59, v45 row_shr:1 row_mask:0xf bank_mask:0xf
	v_pk_mul_f32 v[86:87], v[86:87], v[184:185]
	v_pk_fma_f32 v[126:127], v[110:111], v[54:55], v[64:65]
	v_mov_b32_dpp v34, v40 row_shr:1 row_mask:0xf bank_mask:0xf
	v_mov_b32_dpp v35, v41 row_shr:1 row_mask:0xf bank_mask:0xf
	v_mov_b32_dpp v60, v42 row_shr:1 row_mask:0xf bank_mask:0xf
	v_mov_b32_dpp v61, v43 row_shr:1 row_mask:0xf bank_mask:0xf
	v_pk_mul_f32 v[118:119], v[134:135], v[178:179]
	v_pk_fma_f32 v[122:123], v[86:87], v[56:57], v[62:63]
	v_pk_fma_f32 v[126:127], v[50:51], v[58:59], v[126:127]
	v_mov_b32_dpp v36, v38 row_shr:1 row_mask:0xf bank_mask:0xf
	v_mov_b32_dpp v37, v39 row_shr:1 row_mask:0xf bank_mask:0xf
	v_pk_mul_f32 v[116:117], v[162:163], v[182:183]
	v_pk_fma_f32 v[122:123], v[52:53], v[60:61], v[122:123]
	v_pk_fma_f32 v[34:35], v[46:47], v[34:35], v[126:127]
	v_pk_fma_f32 v[126:127], v[118:119], v[54:55], v[64:65]
	v_pk_fma_f32 v[36:37], v[48:49], v[36:37], v[122:123]
	v_pk_fma_f32 v[122:123], v[116:117], v[56:57], v[62:63]
	v_pk_fma_f32 v[126:127], v[110:111], v[50:51], v[126:127]
	v_pk_fma_f32 v[44:45], v[44:45], v[54:55], v[64:65]
	v_pk_fma_f32 v[122:123], v[86:87], v[52:53], v[122:123]
	v_pk_fma_f32 v[58:59], v[46:47], v[58:59], v[126:127]
	v_pk_fma_f32 v[126:127], v[40:41], v[54:55], v[64:65]
	v_pk_fma_f32 v[42:43], v[42:43], v[56:57], v[62:63]
	v_pk_fma_f32 v[40:41], v[40:41], v[50:51], v[44:45]
	v_exp_f32_e64 v44, -v68
	v_exp_f32_e64 v45, -v69
	v_pk_fma_f32 v[60:61], v[48:49], v[60:61], v[122:123]
	v_pk_fma_f32 v[122:123], v[38:39], v[56:57], v[62:63]
	v_pk_fma_f32 v[38:39], v[38:39], v[52:53], v[42:43]
	v_exp_f32_e64 v42, -v66
	v_exp_f32_e64 v43, -v67
	v_pk_add_f32 v[44:45], v[44:45], 1.0 op_sel_hi:[1,0]
	v_pk_mul_f32 v[36:37], v[68:69], v[36:37]
	v_rcp_f32_e32 v44, v44
	v_pk_add_f32 v[42:43], v[42:43], 1.0 op_sel_hi:[1,0]
	v_rcp_f32_e32 v45, v45
	v_rcp_f32_e32 v42, v42
	v_rcp_f32_e32 v43, v43
	v_pk_mul_f32 v[34:35], v[66:67], v[34:35]
	v_pk_mul_f32 v[36:37], v[44:45], v[36:37]
	v_exp_f32_e64 v44, -v124
	v_exp_f32_e64 v45, -v125
	v_pk_mul_f32 v[34:35], v[42:43], v[34:35]
	v_exp_f32_e64 v42, -v136
	v_exp_f32_e64 v43, -v137
	v_cvt_pk_bf16_f32 v216, v34, v35
	v_cvt_pk_bf16_f32 v217, v36, v37
	global_store_dwordx4 v[94:95], v[214:217], off
	v_pk_add_f32 v[34:35], v[44:45], 1.0 op_sel_hi:[1,0]
	v_pk_add_f32 v[36:37], v[42:43], 1.0 op_sel_hi:[1,0]
	v_rcp_f32_e32 v34, v34
	v_rcp_f32_e32 v35, v35
	v_rcp_f32_e32 v36, v36
	v_rcp_f32_e32 v37, v37
	v_pk_mul_f32 v[42:43], v[124:125], v[60:61]
	v_pk_mul_f32 v[44:45], v[136:137], v[58:59]
	v_pk_mul_f32 v[34:35], v[34:35], v[42:43]
	v_exp_f32_e64 v42, -v120
	v_exp_f32_e64 v43, -v121
	v_pk_mul_f32 v[36:37], v[36:37], v[44:45]
	v_exp_f32_e64 v44, -v88
	v_exp_f32_e64 v45, -v89
	v_cvt_pk_bf16_f32 v220, v36, v37
	v_cvt_pk_bf16_f32 v221, v34, v35
	global_store_dwordx4 v[96:97], v[218:221], off
	v_pk_add_f32 v[36:37], v[42:43], 1.0 op_sel_hi:[1,0]
	v_pk_add_f32 v[34:35], v[44:45], 1.0 op_sel_hi:[1,0]
	v_rcp_f32_e32 v36, v36
	v_rcp_f32_e32 v37, v37
	v_pk_fma_f32 v[126:127], v[118:119], v[50:51], v[126:127]
	v_rcp_f32_e32 v34, v34
	v_rcp_f32_e32 v35, v35
	v_pk_fma_f32 v[122:123], v[116:117], v[52:53], v[122:123]
	v_pk_fma_f32 v[110:111], v[110:111], v[46:47], v[126:127]
	v_pk_fma_f32 v[86:87], v[86:87], v[48:49], v[122:123]
	v_pk_mul_f32 v[42:43], v[120:121], v[110:111]
	v_pk_mul_f32 v[44:45], v[88:89], v[86:87]
	v_pk_mul_f32 v[36:37], v[42:43], v[36:37]
	v_exp_f32_e64 v42, -v114
	v_exp_f32_e64 v43, -v115
	v_pk_mul_f32 v[34:35], v[44:45], v[34:35]
	v_exp_f32_e64 v44, -v112
	v_exp_f32_e64 v45, -v113
	v_cvt_pk_bf16_f32 v224, v36, v37
	v_cvt_pk_bf16_f32 v225, v34, v35
	global_store_dwordx4 v[100:101], v[222:225], off
	v_pk_add_f32 v[36:37], v[42:43], 1.0 op_sel_hi:[1,0]
	v_pk_add_f32 v[34:35], v[44:45], 1.0 op_sel_hi:[1,0]
	v_rcp_f32_e32 v36, v36
	v_rcp_f32_e32 v37, v37
	v_rcp_f32_e32 v34, v34
	v_rcp_f32_e32 v35, v35
	v_pk_fma_f32 v[40:41], v[118:119], v[46:47], v[40:41]
	v_pk_fma_f32 v[38:39], v[116:117], v[48:49], v[38:39]
	v_pk_mul_f32 v[40:41], v[114:115], v[40:41]
	v_pk_mul_f32 v[38:39], v[112:113], v[38:39]
	v_pk_mul_f32 v[36:37], v[40:41], v[36:37]
	v_pk_mul_f32 v[34:35], v[38:39], v[34:35]
	v_cvt_pk_bf16_f32 v228, v36, v37
	v_mov_b32_e32 v38, 0
	v_cvt_pk_bf16_f32 v229, v34, v35
	global_store_dwordx4 v[104:105], v[226:229], off
	v_mov_b32_e32 v34, 0
	v_mov_b32_e32 v39, 0
	v_mov_b32_e32 v40, 0
	v_mov_b32_e32 v41, 0
	v_mov_b32_e32 v42, 0
	v_mov_b32_e32 v43, 0
	v_mov_b32_e32 v44, 0
	v_mov_b32_e32 v45, 0
	s_and_saveexec_b64 s[6:7], vcc
	s_cbranch_execz .LBB0_1417
	ds_read_b128 v[38:41], v186 offset:128
	ds_read_b128 v[42:45], v186 offset:144

.LBB0_1419:
	s_or_b64 exec, exec, s[6:7]
	v_cvt_f32_i32_e32 v23, v23
	v_cvt_f32_i32_e32 v22, v22
	v_cvt_f32_i32_e32 v25, v25
	v_cvt_f32_i32_e32 v24, v24
	v_cvt_f32_i32_e32 v21, v21
	v_cvt_f32_i32_e32 v20, v20
	v_mov_b32_e32 v86, v131
	v_mov_b32_e32 v87, v131
	v_cvt_f32_i32_e32 v17, v17
	v_cvt_f32_i32_e32 v16, v16
	v_cvt_f32_i32_e32 v5, v5
	v_cvt_f32_i32_e32 v4, v4
	v_mov_b32_e32 v88, v131
	v_mov_b32_e32 v89, v131
	v_pk_mul_f32 v[94:95], v[86:87], v[22:23]
	v_pk_fma_f32 v[22:23], v[60:61], v[84:85], v[72:73]
	v_cvt_f32_i32_e32 v15, v15
	v_cvt_f32_i32_e32 v14, v14
	v_cvt_f32_i32_e32 v9, v9
	v_cvt_f32_i32_e32 v8, v8
	v_cvt_f32_i32_e32 v3, v3
	v_cvt_f32_i32_e32 v2, v2
	v_pk_mul_f32 v[24:25], v[88:89], v[24:25]
	v_pk_fma_f32 v[60:61], v[66:67], v[82:83], v[70:71]
	v_pk_fma_f32 v[22:23], v[32:33], v[80:81], v[22:23]
	v_cvt_f32_i32_e32 v67, v19
	v_cvt_f32_i32_e32 v66, v18
	v_mov_b32_e32 v131, v130
	v_pk_fma_f32 v[32:33], v[32:33], v[84:85], v[72:73]
	v_cvt_f32_i32_e32 v13, v13
	v_cvt_f32_i32_e32 v12, v12
	v_cvt_f32_i32_e32 v7, v7
	v_cvt_f32_i32_e32 v6, v6
	v_pk_fma_f32 v[22:23], v[24:25], v[74:75], v[22:23]
	v_pk_mul_f32 v[20:21], v[130:131], v[20:21]
	v_pk_fma_f32 v[32:33], v[24:25], v[80:81], v[32:33]
	v_pk_fma_f32 v[24:25], v[24:25], v[84:85], v[72:73]
	v_cvt_f32_i32_e32 v11, v11
	v_cvt_f32_i32_e32 v10, v10
	v_mov_b32_e32 v68, v130
	v_mov_b32_e32 v69, v130
	v_pk_fma_f32 v[32:33], v[20:21], v[74:75], v[32:33]
	v_pk_fma_f32 v[24:25], v[20:21], v[80:81], v[24:25]
	v_pk_fma_f32 v[20:21], v[20:21], v[84:85], v[72:73]
	v_pk_mul_f32 v[4:5], v[132:133], v[4:5]
	v_pk_mul_f32 v[16:17], v[130:131], v[16:17]
	v_pk_fma_f32 v[60:61], v[58:59], v[78:79], v[60:61]
	v_pk_fma_f32 v[58:59], v[58:59], v[82:83], v[70:71]
	v_pk_fma_f32 v[20:21], v[80:81], v[44:45], v[20:21]
	v_pk_mul_f32 v[8:9], v[30:31], v[8:9]
	v_pk_mul_f32 v[2:3], v[90:91], v[2:3]
	s_waitcnt lgkmcnt(0)
	v_mov_b32_dpp v28, v4 row_shr:1 row_mask:0xf bank_mask:0xf
	v_mov_b32_dpp v29, v5 row_shr:1 row_mask:0xf bank_mask:0xf
	v_pk_mul_f32 v[14:15], v[68:69], v[14:15]
	v_pk_fma_f32 v[30:31], v[16:17], v[56:57], v[62:63]
	v_pk_fma_f32 v[18:19], v[94:95], v[76:77], v[60:61]
	v_pk_mul_f32 v[60:61], v[68:69], v[66:67]
	v_pk_fma_f32 v[58:59], v[94:95], v[78:79], v[58:59]
	v_pk_fma_f32 v[66:67], v[94:95], v[82:83], v[70:71]
	v_pk_fma_f32 v[20:21], v[74:75], v[40:41], v[20:21]
	v_pk_mul_f32 v[6:7], v[92:93], v[6:7]
	v_mov_b32_dpp v26, v2 row_shr:1 row_mask:0xf bank_mask:0xf
	v_mov_b32_dpp v27, v3 row_shr:1 row_mask:0xf bank_mask:0xf
	v_mov_b32_dpp v36, v8 row_shr:1 row_mask:0xf bank_mask:0xf
	v_mov_b32_dpp v37, v9 row_shr:1 row_mask:0xf bank_mask:0xf
	v_pk_mul_f32 v[12:13], v[88:89], v[12:13]
	v_pk_fma_f32 v[40:41], v[14:15], v[54:55], v[64:65]
	v_pk_fma_f32 v[30:31], v[52:53], v[28:29], v[30:31]
	v_pk_fma_f32 v[58:59], v[60:61], v[76:77], v[58:59]
	v_pk_fma_f32 v[66:67], v[60:61], v[78:79], v[66:67]
	v_pk_fma_f32 v[60:61], v[60:61], v[82:83], v[70:71]
	v_mov_b32_dpp v34, v6 row_shr:1 row_mask:0xf bank_mask:0xf
	v_mov_b32_dpp v35, v7 row_shr:1 row_mask:0xf bank_mask:0xf
	v_pk_mul_f32 v[10:11], v[86:87], v[10:11]
	v_pk_fma_f32 v[40:41], v[50:51], v[26:27], v[40:41]
	v_pk_fma_f32 v[30:31], v[48:49], v[36:37], v[30:31]
	v_pk_fma_f32 v[36:37], v[12:13], v[56:57], v[62:63]
	v_pk_fma_f32 v[66:67], v[76:77], v[42:43], v[66:67]
	v_pk_fma_f32 v[42:43], v[78:79], v[42:43], v[60:61]
	v_pk_fma_f32 v[34:35], v[46:47], v[34:35], v[40:41]
	v_pk_fma_f32 v[40:41], v[10:11], v[54:55], v[64:65]
	v_pk_fma_f32 v[36:37], v[16:17], v[52:53], v[36:37]
	v_pk_fma_f32 v[4:5], v[4:5], v[56:57], v[62:63]
	v_pk_fma_f32 v[38:39], v[76:77], v[38:39], v[42:43]
	v_pk_fma_f32 v[40:41], v[14:15], v[50:51], v[40:41]
	v_pk_fma_f32 v[28:29], v[48:49], v[28:29], v[36:37]
	v_pk_fma_f32 v[36:37], v[8:9], v[56:57], v[62:63]
	v_pk_fma_f32 v[2:3], v[2:3], v[54:55], v[64:65]
	v_pk_fma_f32 v[4:5], v[8:9], v[52:53], v[4:5]
	v_exp_f32_e64 v8, -v20
	v_exp_f32_e64 v9, -v21
	v_pk_fma_f32 v[26:27], v[46:47], v[26:27], v[40:41]
	v_pk_fma_f32 v[40:41], v[6:7], v[54:55], v[64:65]
	v_pk_fma_f32 v[2:3], v[6:7], v[50:51], v[2:3]
	v_exp_f32_e64 v6, -v38
	v_exp_f32_e64 v7, -v39
	v_pk_add_f32 v[8:9], v[8:9], 1.0 op_sel_hi:[1,0]
	v_pk_fma_f32 v[40:41], v[10:11], v[50:51], v[40:41]
	v_rcp_f32_e32 v8, v8
	v_pk_add_f32 v[6:7], v[6:7], 1.0 op_sel_hi:[1,0]
	v_rcp_f32_e32 v9, v9
	v_rcp_f32_e32 v6, v6
	v_rcp_f32_e32 v7, v7
	v_pk_fma_f32 v[2:3], v[10:11], v[46:47], v[2:3]
	v_pk_mul_f32 v[10:11], v[20:21], v[30:31]
	v_pk_fma_f32 v[24:25], v[74:75], v[44:45], v[24:25]
	v_pk_fma_f32 v[36:37], v[12:13], v[52:53], v[36:37]
	v_pk_fma_f32 v[4:5], v[12:13], v[48:49], v[4:5]
	v_pk_mul_f32 v[12:13], v[38:39], v[34:35]
	v_pk_mul_f32 v[8:9], v[8:9], v[10:11]
	v_exp_f32_e64 v10, -v66
	v_exp_f32_e64 v11, -v67
	v_pk_mul_f32 v[6:7], v[6:7], v[12:13]
	v_exp_f32_e64 v12, -v24
	v_exp_f32_e64 v13, -v25
	v_cvt_pk_bf16_f32 v244, v6, v7
	v_cvt_pk_bf16_f32 v245, v8, v9
	v_pk_add_f32 v[8:9], v[10:11], 1.0 op_sel_hi:[1,0]
	global_store_dwordx4 v[98:99], v[242:245], off
	v_pk_add_f32 v[6:7], v[12:13], 1.0 op_sel_hi:[1,0]
	v_rcp_f32_e32 v8, v8
	v_rcp_f32_e32 v9, v9
	v_rcp_f32_e32 v6, v6
	v_rcp_f32_e32 v7, v7
	v_pk_mul_f32 v[12:13], v[66:67], v[26:27]
	v_pk_mul_f32 v[10:11], v[24:25], v[28:29]
	v_pk_mul_f32 v[8:9], v[8:9], v[12:13]
	v_exp_f32_e64 v12, -v32
	v_exp_f32_e64 v13, -v33
	v_pk_mul_f32 v[6:7], v[6:7], v[10:11]
	v_exp_f32_e64 v10, -v58
	v_exp_f32_e64 v11, -v59
	v_cvt_pk_bf16_f32 v248, v8, v9
	v_cvt_pk_bf16_f32 v249, v6, v7
	v_pk_add_f32 v[6:7], v[12:13], 1.0 op_sel_hi:[1,0]
	global_store_dwordx4 v[102:103], v[246:249], off
	v_pk_add_f32 v[8:9], v[10:11], 1.0 op_sel_hi:[1,0]
	v_rcp_f32_e32 v6, v6
	v_rcp_f32_e32 v7, v7
	v_rcp_f32_e32 v8, v8
	v_rcp_f32_e32 v9, v9
	v_pk_fma_f32 v[16:17], v[16:17], v[48:49], v[36:37]
	v_pk_fma_f32 v[14:15], v[14:15], v[46:47], v[40:41]
	v_pk_mul_f32 v[10:11], v[32:33], v[16:17]
	v_pk_mul_f32 v[12:13], v[58:59], v[14:15]
	v_pk_mul_f32 v[6:7], v[10:11], v[6:7]
	v_exp_f32_e64 v10, -v18
	v_exp_f32_e64 v11, -v19
	v_pk_mul_f32 v[8:9], v[12:13], v[8:9]
	v_exp_f32_e64 v12, -v22
	v_exp_f32_e64 v13, -v23
	v_cvt_pk_bf16_f32 v252, v8, v9
	v_cvt_pk_bf16_f32 v253, v6, v7
	global_store_dwordx4 v[106:107], v[250:253], off
	v_pk_add_f32 v[8:9], v[10:11], 1.0 op_sel_hi:[1,0]
	v_pk_add_f32 v[6:7], v[12:13], 1.0 op_sel_hi:[1,0]
	v_rcp_f32_e32 v8, v8
	v_rcp_f32_e32 v9, v9
	v_rcp_f32_e32 v6, v6
	v_rcp_f32_e32 v7, v7
	v_pk_mul_f32 v[2:3], v[18:19], v[2:3]
	v_pk_mul_f32 v[4:5], v[22:23], v[4:5]
	v_pk_mul_f32 v[2:3], v[2:3], v[8:9]
	v_pk_mul_f32 v[4:5], v[4:5], v[6:7]
	v_cvt_pk_bf16_f32 v2, v2, v3
	s_andn2_b64 vcc, exec, s[2:3]
	v_cvt_pk_bf16_f32 v3, v4, v5
	global_store_dwordx2 v[108:109], v[2:3], off offset:8
	s_mov_b64 s[2:3], -1
	s_cbranch_vccnz .LBB0_1363
	s_and_b32 s2, s8, 1
	v_lshl_add_u32 v2, s30, 7, v1
	s_mul_i32 s3, s2, 0x1400
	v_ashrrev_i32_e32 v3, 31, v2
	s_add_i32 s3, s27, s3
	v_lshlrev_b64 v[2:3], 2, v[2:3]
	v_lshl_add_u64 v[4:5], v[138:139], 0, v[2:3]
	s_mov_b32 m0, s3
	v_lshl_add_u64 v[2:3], v[140:141], 0, v[2:3]
	global_load_lds_dword v[4:5], off
	s_add_i32 m0, s3, 0x800
	s_andn2_b64 vcc, exec, s[10:11]
	global_load_lds_dword v[2:3], off
	s_cbranch_vccnz .LBB0_1422
	s_lshl_b32 s6, s30, 8
	s_ashr_i32 s7, s6, 31
	v_lshl_add_u64 v[2:3], s[6:7], 2, v[150:151]
	s_add_i32 m0, s3, 0x1000
	s_nop 0
	global_load_lds_dword v[2:3], off

.LBB0_2096:
	s_or_b64 exec, exec, s[18:19]
	v_pk_mul_f32 v[106:107], v[106:107], v[114:115]
	v_pk_mul_f32 v[104:105], v[104:105], v[116:117]
	v_pk_mul_f32 v[200:201], v[112:113], v[116:117]
	v_pk_mul_f32 v[112:113], v[110:111], v[114:115]
	v_pk_mul_f32 v[202:203], v[108:109], v[116:117]
	v_pk_mul_f32 v[116:117], v[106:107], s[24:25] op_sel_hi:[1,0]
	v_pk_mul_f32 v[204:205], v[98:99], s[24:25] op_sel_hi:[1,0]
	v_pk_mul_f32 v[98:99], v[162:163], v[194:195] op_sel_hi:[0,1]
	v_pk_mul_f32 v[102:103], v[102:103], v[114:115]
	v_pk_mul_f32 v[110:111], v[104:105], s[24:25] op_sel_hi:[1,0]
	v_pk_mul_f32 v[112:113], v[112:113], s[24:25] op_sel_hi:[1,0]
	v_pk_mul_f32 v[114:115], v[200:201], s[24:25] op_sel_hi:[1,0]
	v_pk_mul_f32 v[200:201], v[202:203], s[24:25] op_sel_hi:[1,0]
	v_pk_mul_f32 v[202:203], v[100:101], s[24:25] op_sel_hi:[1,0]
	v_pk_mul_f32 v[100:101], v[162:163], v[192:193] op_sel_hi:[0,1]
	v_pk_mul_f32 v[104:105], v[162:163], v[188:189] op_sel:[1,0]
	v_pk_fma_f32 v[188:189], v[98:99], v[116:117], v[204:205]
	v_pk_mul_f32 v[108:109], v[102:103], s[24:25] op_sel_hi:[1,0]
	v_pk_mul_f32 v[102:103], v[162:163], v[190:191] op_sel:[1,0]
	v_pk_fma_f32 v[106:107], v[100:101], v[200:201], v[202:203]
	v_pk_fma_f32 v[188:189], v[112:113], v[90:91], v[188:189]
	v_pk_fma_f32 v[106:107], v[114:115], v[92:93], v[106:107]
	v_pk_fma_f32 v[94:95], v[108:109], v[94:95], v[188:189]
	v_pk_fma_f32 v[188:189], v[102:103], v[116:117], v[204:205]
	v_pk_fma_f32 v[96:97], v[110:111], v[96:97], v[106:107]
	v_pk_fma_f32 v[106:107], v[104:105], v[200:201], v[202:203]
	v_pk_fma_f32 v[188:189], v[98:99], v[112:113], v[188:189]
	v_pk_fma_f32 v[106:107], v[100:101], v[114:115], v[106:107]
	v_pk_fma_f32 v[90:91], v[108:109], v[90:91], v[188:189]
	v_pk_fma_f32 v[188:189], v[224:225], v[116:117], v[204:205]
	v_pk_fma_f32 v[92:93], v[110:111], v[92:93], v[106:107]
	v_pk_fma_f32 v[106:107], v[222:223], v[200:201], v[202:203]
	v_pk_fma_f32 v[188:189], v[102:103], v[112:113], v[188:189]
	v_pk_fma_f32 v[106:107], v[104:105], v[114:115], v[106:107]
	v_pk_fma_f32 v[190:191], v[98:99], v[108:109], v[188:189]
	v_pk_fma_f32 v[98:99], v[226:227], v[200:201], v[202:203]
	v_pk_fma_f32 v[100:101], v[100:101], v[110:111], v[106:107]
	v_pk_fma_f32 v[106:107], v[228:229], v[116:117], v[204:205]
	v_pk_fma_f32 v[98:99], v[222:223], v[114:115], v[98:99]
	v_pk_mul_f32 v[70:71], v[70:71], v[82:83]
	v_mov_b32_e32 v196, v165
	v_mov_b32_e32 v197, v165
	v_pk_fma_f32 v[106:107], v[224:225], v[112:113], v[106:107]
	v_pk_fma_f32 v[104:105], v[104:105], v[110:111], v[98:99]
	v_pk_mul_f32 v[80:81], v[80:81], v[84:85]
	v_pk_mul_f32 v[78:79], v[78:79], v[82:83]
	v_pk_mul_f32 v[98:99], v[76:77], v[84:85]
	v_pk_mul_f32 v[74:75], v[74:75], v[82:83]
	v_pk_mul_f32 v[72:73], v[72:73], v[84:85]
	v_pk_mul_f32 v[84:85], v[70:71], s[26:27] op_sel_hi:[1,0]
	v_mov_b32_e32 v70, v165
	v_mov_b32_e32 v71, v165
	v_mov_b32_e32 v198, v164
	v_mov_b32_e32 v199, v164
	v_pk_fma_f32 v[192:193], v[102:103], v[108:109], v[106:107]
	v_pk_mul_f32 v[76:77], v[78:79], s[26:27] op_sel_hi:[1,0]
	v_pk_mul_f32 v[78:79], v[80:81], s[26:27] op_sel_hi:[1,0]
	v_pk_mul_f32 v[80:81], v[74:75], s[26:27] op_sel_hi:[1,0]
	v_pk_mul_f32 v[82:83], v[98:99], s[26:27] op_sel_hi:[1,0]
	v_pk_mul_f32 v[98:99], v[72:73], s[26:27] op_sel_hi:[1,0]
	v_pk_mul_f32 v[102:103], v[68:69], s[26:27] op_sel_hi:[1,0]
	v_pk_mul_f32 v[106:107], v[66:67], s[26:27] op_sel_hi:[1,0]
	v_mov_b32_e32 v66, v164
	v_mov_b32_e32 v67, v164
	v_pk_mul_f32 v[70:71], v[70:71], v[210:211]
	v_pk_mul_f32 v[72:73], v[196:197], v[206:207]
	v_pk_mul_f32 v[74:75], v[162:163], v[220:221] op_sel_hi:[0,1]
	v_pk_mul_f32 v[194:195], v[162:163], v[218:219] op_sel_hi:[0,1]
	v_pk_mul_f32 v[66:67], v[66:67], v[212:213]
	v_pk_mul_f32 v[68:69], v[198:199], v[208:209]
	s_waitcnt lgkmcnt(0)
	v_mov_b32_dpp v86, v72 row_shr:1 row_mask:0xf bank_mask:0xf
	v_mov_b32_dpp v87, v73 row_shr:1 row_mask:0xf bank_mask:0xf
	v_mov_b32_dpp v88, v70 row_shr:1 row_mask:0xf bank_mask:0xf
	v_mov_b32_dpp v89, v71 row_shr:1 row_mask:0xf bank_mask:0xf
	v_pk_fma_f32 v[210:211], v[194:195], v[98:99], v[102:103]
	v_pk_fma_f32 v[212:213], v[74:75], v[84:85], v[106:107]
	v_mov_b32_dpp v62, v68 row_shr:1 row_mask:0xf bank_mask:0xf
	v_mov_b32_dpp v63, v69 row_shr:1 row_mask:0xf bank_mask:0xf
	v_mov_b32_dpp v64, v66 row_shr:1 row_mask:0xf bank_mask:0xf
	v_mov_b32_dpp v65, v67 row_shr:1 row_mask:0xf bank_mask:0xf
	v_pk_mul_f32 v[206:207], v[162:163], v[216:217] op_sel:[1,0]
	v_pk_mul_f32 v[208:209], v[162:163], v[214:215] op_sel:[1,0]
	v_pk_fma_f32 v[212:213], v[80:81], v[86:87], v[212:213]
	v_pk_fma_f32 v[210:211], v[82:83], v[88:89], v[210:211]
	v_pk_fma_f32 v[62:63], v[76:77], v[62:63], v[212:213]
	v_pk_fma_f32 v[64:65], v[78:79], v[64:65], v[210:211]
	v_pk_fma_f32 v[210:211], v[208:209], v[98:99], v[102:103]
	v_pk_fma_f32 v[212:213], v[206:207], v[84:85], v[106:107]
	v_pk_fma_f32 v[210:211], v[194:195], v[82:83], v[210:211]
	v_pk_fma_f32 v[212:213], v[74:75], v[80:81], v[212:213]
	v_pk_fma_f32 v[70:71], v[70:71], v[98:99], v[102:103]
	v_pk_fma_f32 v[72:73], v[72:73], v[84:85], v[106:107]
	v_pk_fma_f32 v[88:89], v[78:79], v[88:89], v[210:211]
	v_pk_fma_f32 v[86:87], v[76:77], v[86:87], v[212:213]
	v_pk_fma_f32 v[210:211], v[66:67], v[98:99], v[102:103]
	v_pk_fma_f32 v[212:213], v[68:69], v[84:85], v[106:107]
	v_pk_fma_f32 v[66:67], v[66:67], v[82:83], v[70:71]
	v_pk_fma_f32 v[68:69], v[68:69], v[80:81], v[72:73]
	v_exp_f32_e64 v70, -v94
	v_exp_f32_e64 v72, -v96
	v_exp_f32_e64 v73, -v97
	v_exp_f32_e64 v71, -v95
	s_lshl_b32 s18, s38, 8
	v_pk_mul_f32 v[62:63], v[94:95], v[62:63]
	v_pk_add_f32 v[72:73], v[72:73], 1.0 op_sel_hi:[1,0]
	v_pk_add_f32 v[70:71], v[70:71], 1.0 op_sel_hi:[1,0]
	v_rcp_f32_e32 v72, v72
	v_rcp_f32_e32 v70, v70
	v_rcp_f32_e32 v73, v73
	v_rcp_f32_e32 v71, v71
	v_pk_mul_f32 v[64:65], v[96:97], v[64:65]
	s_add_i32 s18, s18, s61
	v_pk_mul_f32 v[64:65], v[72:73], v[64:65]
	v_pk_mul_f32 v[62:63], v[70:71], v[62:63]
	v_exp_f32_e64 v72, -v90
	v_exp_f32_e64 v96, -v92
	v_exp_f32_e64 v97, -v93
	v_exp_f32_e64 v73, -v91
	v_add_u32_e32 v188, s18, v243
	v_pk_fma_f32 v[210:211], v[208:209], v[82:83], v[210:211]
	v_pk_fma_f32 v[212:213], v[206:207], v[80:81], v[212:213]
	v_cvt_pk_bf16_f32 v214, v62, v63
	v_cvt_pk_bf16_f32 v215, v64, v65
	v_mov_b64_e32 v[64:65], s[58:59]
	v_pk_fma_f32 v[194:195], v[194:195], v[78:79], v[210:211]
	v_pk_fma_f32 v[210:211], v[74:75], v[76:77], v[212:213]
	v_mad_i64_i32 v[70:71], s[18:19], v188, s84, v[64:65]
	v_lshlrev_b64 v[74:75], 1, v[186:187]
	v_lshl_add_u64 v[94:95], v[70:71], 0, v[74:75]
	v_pk_add_f32 v[62:63], v[96:97], 1.0 op_sel_hi:[1,0]
	v_pk_add_f32 v[70:71], v[72:73], 1.0 op_sel_hi:[1,0]
	v_rcp_f32_e32 v62, v62
	v_rcp_f32_e32 v70, v70
	v_rcp_f32_e32 v63, v63
	v_rcp_f32_e32 v71, v71
	v_pk_mul_f32 v[72:73], v[90:91], v[86:87]
	v_pk_mul_f32 v[86:87], v[92:93], v[88:89]
	v_pk_fma_f32 v[66:67], v[208:209], v[78:79], v[66:67]
	v_pk_mul_f32 v[62:63], v[62:63], v[86:87]
	v_pk_mul_f32 v[70:71], v[70:71], v[72:73]
	v_exp_f32_e64 v72, -v190
	v_exp_f32_e64 v86, -v100
	v_exp_f32_e64 v87, -v101
	v_exp_f32_e64 v73, -v191
	v_cvt_pk_bf16_f32 v218, v70, v71
	v_cvt_pk_bf16_f32 v219, v62, v63
	v_or_b32_e32 v62, 1, v188
	v_mad_i64_i32 v[62:63], s[18:19], v62, s84, v[64:65]
	v_lshl_add_u64 v[96:97], v[62:63], 0, v[74:75]
	v_pk_add_f32 v[62:63], v[86:87], 1.0 op_sel_hi:[1,0]
	v_pk_add_f32 v[70:71], v[72:73], 1.0 op_sel_hi:[1,0]
	v_rcp_f32_e32 v62, v62
	v_rcp_f32_e32 v70, v70
	v_rcp_f32_e32 v63, v63
	v_rcp_f32_e32 v71, v71
	v_pk_mul_f32 v[72:73], v[190:191], v[210:211]
	v_pk_mul_f32 v[86:87], v[100:101], v[194:195]
	v_pk_fma_f32 v[68:69], v[206:207], v[76:77], v[68:69]
	v_pk_mul_f32 v[62:63], v[86:87], v[62:63]
	v_pk_mul_f32 v[70:71], v[72:73], v[70:71]
	v_exp_f32_e64 v72, -v192
	v_exp_f32_e64 v86, -v104
	v_exp_f32_e64 v87, -v105
	v_exp_f32_e64 v73, -v193
	v_cvt_pk_bf16_f32 v222, v70, v71
	v_cvt_pk_bf16_f32 v223, v62, v63
	v_or_b32_e32 v62, 2, v188
	v_mad_i64_i32 v[62:63], s[18:19], v62, s84, v[64:65]
	v_lshl_add_u64 v[100:101], v[62:63], 0, v[74:75]
	v_pk_add_f32 v[62:63], v[86:87], 1.0 op_sel_hi:[1,0]
	v_pk_add_f32 v[70:71], v[72:73], 1.0 op_sel_hi:[1,0]
	v_rcp_f32_e32 v62, v62
	v_rcp_f32_e32 v70, v70
	v_rcp_f32_e32 v63, v63
	v_rcp_f32_e32 v71, v71
	v_pk_mul_f32 v[68:69], v[192:193], v[68:69]
	v_pk_mul_f32 v[66:67], v[104:105], v[66:67]
	v_lshl_add_u32 v186, v239, 5, v233
	v_pk_mul_f32 v[62:63], v[66:67], v[62:63]
	v_pk_mul_f32 v[66:67], v[68:69], v[70:71]
	v_mov_b32_e32 v70, 0
	v_cvt_pk_bf16_f32 v226, v66, v67
	v_cvt_pk_bf16_f32 v227, v62, v63
	v_or_b32_e32 v62, 3, v188
	v_mad_i64_i32 v[62:63], s[18:19], v62, s84, v[64:65]
	v_lshl_add_u64 v[104:105], v[62:63], 0, v[74:75]
	v_mov_b32_e32 v62, 0
	v_mov_b32_e32 v71, 0
	v_mov_b32_e32 v72, 0
	v_mov_b32_e32 v73, 0
	v_mov_b32_e32 v66, 0
	v_mov_b32_e32 v67, 0
	v_mov_b32_e32 v68, 0
	v_mov_b32_e32 v69, 0
	s_and_saveexec_b64 s[18:19], vcc
	s_cbranch_execz .LBB0_2098
	ds_read_b128 v[70:73], v186
	ds_read_b128 v[66:69], v186 offset:16

.LBB0_2100:
	s_or_b64 exec, exec, s[18:19]
	v_cvt_f32_i32_e32 v57, v57
	v_cvt_f32_i32_e32 v56, v56
	v_cvt_f32_i32_e32 v55, v55
	v_cvt_f32_i32_e32 v54, v54
	v_cvt_f32_i32_e32 v53, v53
	v_cvt_f32_i32_e32 v52, v52
	v_cvt_f32_i32_e32 v51, v51
	v_cvt_f32_i32_e32 v50, v50
	v_pk_mul_f32 v[56:57], v[130:131], v[56:57] op_sel_hi:[0,1]
	v_pk_fma_f32 v[190:191], v[56:57], v[200:201], v[202:203]
	v_pk_mul_f32 v[54:55], v[130:131], v[54:55] op_sel_hi:[0,1]
	v_pk_mul_f32 v[52:53], v[130:131], v[52:53] op_sel:[1,0]
	v_pk_fma_f32 v[190:191], v[114:115], v[68:69], v[190:191]
	v_pk_fma_f32 v[192:193], v[54:55], v[116:117], v[204:205]
	v_pk_fma_f32 v[72:73], v[110:111], v[72:73], v[190:191]
	v_pk_fma_f32 v[190:191], v[52:53], v[200:201], v[202:203]
	v_cvt_f32_i32_e32 v41, v41
	v_cvt_f32_i32_e32 v40, v40
	v_pk_mul_f32 v[50:51], v[130:131], v[50:51] op_sel:[1,0]
	v_pk_fma_f32 v[192:193], v[112:113], v[66:67], v[192:193]
	v_pk_fma_f32 v[190:191], v[56:57], v[114:115], v[190:191]
	v_pk_fma_f32 v[134:135], v[134:135], v[200:201], v[202:203]
	v_cvt_f32_i32_e32 v49, v49
	v_cvt_f32_i32_e32 v48, v48
	v_cvt_f32_i32_e32 v47, v47
	v_cvt_f32_i32_e32 v46, v46
	v_cvt_f32_i32_e32 v35, v35
	v_cvt_f32_i32_e32 v37, v37
	v_cvt_f32_i32_e32 v36, v36
	v_cvt_f32_i32_e32 v34, v34
	v_pk_fma_f32 v[70:71], v[108:109], v[70:71], v[192:193]
	v_pk_fma_f32 v[192:193], v[50:51], v[116:117], v[204:205]
	v_pk_fma_f32 v[68:69], v[110:111], v[68:69], v[190:191]
	v_pk_fma_f32 v[190:191], v[86:87], v[200:201], v[202:203]
	v_pk_fma_f32 v[86:87], v[86:87], v[114:115], v[134:135]
	v_cvt_f32_i32_e32 v39, v39
	v_cvt_f32_i32_e32 v38, v38
	v_pk_fma_f32 v[192:193], v[54:55], v[112:113], v[192:193]
	v_pk_fma_f32 v[190:191], v[52:53], v[114:115], v[190:191]
	v_pk_fma_f32 v[52:53], v[52:53], v[110:111], v[86:87]
	v_cvt_f32_i32_e32 v45, v45
	v_cvt_f32_i32_e32 v44, v44
	v_cvt_f32_i32_e32 v43, v43
	v_cvt_f32_i32_e32 v42, v42
	v_mov_b32_e32 v86, v132
	v_mov_b32_e32 v87, v132
	v_mov_b32_e32 v90, v133
	v_mov_b32_e32 v91, v133
	v_pk_fma_f32 v[66:67], v[108:109], v[66:67], v[192:193]
	v_pk_fma_f32 v[192:193], v[88:89], v[116:117], v[204:205]
	v_pk_fma_f32 v[116:117], v[136:137], v[116:117], v[204:205]
	v_pk_mul_f32 v[40:41], v[86:87], v[40:41]
	v_mov_b32_e32 v86, v133
	v_mov_b32_e32 v87, v133
	v_mov_b32_e32 v92, v132
	v_mov_b32_e32 v93, v132
	v_pk_fma_f32 v[88:89], v[88:89], v[112:113], v[116:117]
	v_pk_mul_f32 v[36:37], v[86:87], v[36:37]
	v_pk_mul_f32 v[34:35], v[90:91], v[34:35]
	v_pk_mul_f32 v[46:47], v[130:131], v[46:47] op_sel_hi:[0,1]
	v_pk_mul_f32 v[48:49], v[130:131], v[48:49] op_sel_hi:[0,1]
	v_pk_fma_f32 v[192:193], v[50:51], v[112:113], v[192:193]
	v_pk_fma_f32 v[50:51], v[50:51], v[108:109], v[88:89]
	v_pk_mul_f32 v[38:39], v[92:93], v[38:39]
	s_waitcnt lgkmcnt(0)
	v_mov_b32_dpp v58, v34 row_shr:1 row_mask:0xf bank_mask:0xf
	v_mov_b32_dpp v59, v35 row_shr:1 row_mask:0xf bank_mask:0xf
	v_mov_b32_dpp v60, v36 row_shr:1 row_mask:0xf bank_mask:0xf
	v_mov_b32_dpp v61, v37 row_shr:1 row_mask:0xf bank_mask:0xf
	v_pk_fma_f32 v[86:87], v[48:49], v[98:99], v[102:103]
	v_pk_fma_f32 v[88:89], v[46:47], v[84:85], v[106:107]
	v_mov_b32_dpp v62, v38 row_shr:1 row_mask:0xf bank_mask:0xf
	v_mov_b32_dpp v63, v39 row_shr:1 row_mask:0xf bank_mask:0xf
	v_mov_b32_dpp v64, v40 row_shr:1 row_mask:0xf bank_mask:0xf
	v_mov_b32_dpp v65, v41 row_shr:1 row_mask:0xf bank_mask:0xf
	v_pk_mul_f32 v[42:43], v[130:131], v[42:43] op_sel:[1,0]
	v_pk_mul_f32 v[44:45], v[130:131], v[44:45] op_sel:[1,0]
	v_pk_fma_f32 v[86:87], v[82:83], v[60:61], v[86:87]
	v_pk_fma_f32 v[88:89], v[80:81], v[58:59], v[88:89]
	v_pk_fma_f32 v[64:65], v[78:79], v[64:65], v[86:87]
	v_pk_fma_f32 v[62:63], v[76:77], v[62:63], v[88:89]
	v_pk_fma_f32 v[86:87], v[44:45], v[98:99], v[102:103]
	v_pk_fma_f32 v[88:89], v[42:43], v[84:85], v[106:107]
	v_pk_fma_f32 v[86:87], v[48:49], v[82:83], v[86:87]
	v_pk_fma_f32 v[88:89], v[46:47], v[80:81], v[88:89]
	v_pk_fma_f32 v[36:37], v[36:37], v[98:99], v[102:103]
	v_pk_fma_f32 v[34:35], v[34:35], v[84:85], v[106:107]
	v_pk_fma_f32 v[60:61], v[78:79], v[60:61], v[86:87]
	v_pk_fma_f32 v[58:59], v[76:77], v[58:59], v[88:89]
	v_pk_fma_f32 v[86:87], v[40:41], v[98:99], v[102:103]
	v_pk_fma_f32 v[88:89], v[38:39], v[84:85], v[106:107]
	v_pk_fma_f32 v[36:37], v[40:41], v[82:83], v[36:37]
	v_pk_fma_f32 v[34:35], v[38:39], v[80:81], v[34:35]
	v_exp_f32_e64 v38, -v70
	v_exp_f32_e64 v40, -v72
	v_exp_f32_e64 v41, -v73
	v_exp_f32_e64 v39, -v71
	v_pk_fma_f32 v[88:89], v[42:43], v[80:81], v[88:89]
	v_pk_fma_f32 v[86:87], v[44:45], v[82:83], v[86:87]
	v_pk_add_f32 v[40:41], v[40:41], 1.0 op_sel_hi:[1,0]
	v_pk_add_f32 v[38:39], v[38:39], 1.0 op_sel_hi:[1,0]
	v_rcp_f32_e32 v40, v40
	v_rcp_f32_e32 v38, v38
	v_rcp_f32_e32 v41, v41
	v_rcp_f32_e32 v39, v39
	v_pk_fma_f32 v[36:37], v[44:45], v[78:79], v[36:37]
	v_pk_fma_f32 v[34:35], v[42:43], v[76:77], v[34:35]
	v_pk_mul_f32 v[42:43], v[72:73], v[64:65]
	v_pk_mul_f32 v[44:45], v[70:71], v[62:63]
	v_pk_mul_f32 v[40:41], v[40:41], v[42:43]
	v_pk_mul_f32 v[38:39], v[38:39], v[44:45]
	v_exp_f32_e64 v44, -v66
	v_exp_f32_e64 v62, -v68
	v_exp_f32_e64 v63, -v69
	v_exp_f32_e64 v45, -v67
	v_pk_fma_f32 v[46:47], v[46:47], v[76:77], v[88:89]
	v_add_u32_e32 v76, 0x80, v188
	v_cvt_pk_bf16_f32 v242, v38, v39
	v_cvt_pk_bf16_f32 v243, v40, v41
	v_mov_b64_e32 v[40:41], s[58:59]
	v_mad_i64_i32 v[42:43], s[18:19], v76, s84, v[40:41]
	v_lshl_add_u64 v[98:99], v[42:43], 0, v[74:75]
	v_pk_add_f32 v[38:39], v[62:63], 1.0 op_sel_hi:[1,0]
	v_pk_add_f32 v[42:43], v[44:45], 1.0 op_sel_hi:[1,0]
	v_rcp_f32_e32 v38, v38
	v_rcp_f32_e32 v42, v42
	v_rcp_f32_e32 v39, v39
	v_rcp_f32_e32 v43, v43
	v_pk_fma_f32 v[56:57], v[56:57], v[110:111], v[190:191]
	v_pk_fma_f32 v[54:55], v[54:55], v[108:109], v[192:193]
	v_pk_mul_f32 v[44:45], v[68:69], v[60:61]
	v_pk_mul_f32 v[58:59], v[66:67], v[58:59]
	v_pk_mul_f32 v[38:39], v[38:39], v[44:45]
	v_pk_mul_f32 v[42:43], v[42:43], v[58:59]
	v_exp_f32_e64 v44, -v54
	v_exp_f32_e64 v58, -v56
	v_exp_f32_e64 v59, -v57
	v_exp_f32_e64 v45, -v55
	v_cvt_pk_bf16_f32 v246, v42, v43
	v_cvt_pk_bf16_f32 v247, v38, v39
	v_add_u32_e32 v38, 0x81, v188
	v_mad_i64_i32 v[38:39], s[18:19], v38, s84, v[40:41]
	v_lshl_add_u64 v[102:103], v[38:39], 0, v[74:75]
	v_pk_add_f32 v[38:39], v[58:59], 1.0 op_sel_hi:[1,0]
	v_pk_add_f32 v[42:43], v[44:45], 1.0 op_sel_hi:[1,0]
	v_rcp_f32_e32 v38, v38
	v_rcp_f32_e32 v42, v42
	v_rcp_f32_e32 v39, v39
	v_rcp_f32_e32 v43, v43
	v_pk_fma_f32 v[48:49], v[48:49], v[78:79], v[86:87]
	v_pk_mul_f32 v[44:45], v[54:55], v[46:47]
	v_pk_mul_f32 v[46:47], v[56:57], v[48:49]
	v_pk_mul_f32 v[42:43], v[44:45], v[42:43]
	v_pk_mul_f32 v[38:39], v[46:47], v[38:39]
	v_exp_f32_e64 v44, -v50
	v_exp_f32_e64 v46, -v52
	v_exp_f32_e64 v47, -v53
	v_exp_f32_e64 v45, -v51
	v_cvt_pk_bf16_f32 v250, v42, v43
	v_cvt_pk_bf16_f32 v251, v38, v39
	v_add_u32_e32 v38, 0x82, v188
	v_mad_i64_i32 v[38:39], s[18:19], v38, s84, v[40:41]
	v_lshl_add_u64 v[106:107], v[38:39], 0, v[74:75]
	v_pk_add_f32 v[38:39], v[46:47], 1.0 op_sel_hi:[1,0]
	v_pk_add_f32 v[42:43], v[44:45], 1.0 op_sel_hi:[1,0]
	v_rcp_f32_e32 v38, v38
	v_rcp_f32_e32 v42, v42
	v_rcp_f32_e32 v39, v39
	v_rcp_f32_e32 v43, v43
	v_pk_mul_f32 v[36:37], v[52:53], v[36:37]
	v_pk_mul_f32 v[34:35], v[50:51], v[34:35]
	v_pk_mul_f32 v[36:37], v[36:37], v[38:39]
	v_pk_mul_f32 v[34:35], v[34:35], v[42:43]
	v_mov_b32_e32 v66, 0
	v_cvt_pk_bf16_f32 v34, v34, v35
	v_cvt_pk_bf16_f32 v35, v36, v37
	v_add_u32_e32 v36, 0x83, v188
	v_mad_i64_i32 v[36:37], s[18:19], v36, s84, v[40:41]
	v_lshl_add_u64 v[108:109], v[36:37], 0, v[74:75]
	global_store_dwordx2 v[108:109], v[34:35], off
	ds_read_b128 v[74:77], v241 offset:16
	ds_read_b128 v[50:53], v241 offset:528
	ds_read_b128 v[82:85], v241 offset:1040
	ds_read_b128 v[46:49], v241 offset:1552
	ds_read_b128 v[78:81], v241 offset:2064
	ds_read_b128 v[42:45], v241 offset:2576
	ds_read_b128 v[70:73], v241 offset:3088
	ds_read_b128 v[38:41], v241 offset:3600
	ds_read_b128 v[86:89], v241 offset:4112
	ds_read_b128 v[54:57], v241 offset:4624
	v_mov_b32_e32 v34, 0
	v_mov_b32_e32 v67, 0
	v_mov_b32_e32 v68, 0
	v_mov_b32_e32 v69, 0
	v_mov_b32_e32 v62, 0
	v_mov_b32_e32 v63, 0
	v_mov_b32_e32 v64, 0
	v_mov_b32_e32 v65, 0
	s_and_saveexec_b64 s[18:19], s[4:5]
	s_cbranch_execz .LBB0_2102
	ds_read_b128 v[66:69], v240 offset:128
	ds_read_b128 v[62:65], v240 offset:144

.LBB0_2104:
	s_or_b64 exec, exec, s[18:19]
	v_pk_mul_f32 v[74:75], v[74:75], v[86:87]
	v_pk_mul_f32 v[82:83], v[82:83], v[86:87]
	v_pk_mul_f32 v[86:87], v[78:79], v[86:87]
	v_pk_mul_f32 v[136:137], v[76:77], v[88:89]
	v_pk_mul_f32 v[84:85], v[84:85], v[88:89]
	v_pk_mul_f32 v[88:89], v[80:81], v[88:89]
	v_pk_mul_f32 v[78:79], v[82:83], s[24:25] op_sel_hi:[1,0]
	v_pk_mul_f32 v[82:83], v[86:87], s[24:25] op_sel_hi:[1,0]
	v_mov_b32_e32 v86, v162
	v_mov_b32_e32 v87, v162
	v_mov_b32_e32 v128, v162
	v_mov_b32_e32 v129, v162
	v_pk_mul_f32 v[80:81], v[84:85], s[24:25] op_sel_hi:[1,0]
	v_pk_mul_f32 v[84:85], v[88:89], s[24:25] op_sel_hi:[1,0]
	v_pk_mul_f32 v[72:73], v[72:73], s[24:25] op_sel_hi:[1,0]
	v_pk_mul_f32 v[88:89], v[86:87], v[124:125]
	v_pk_mul_f32 v[70:71], v[70:71], s[24:25] op_sel_hi:[1,0]
	v_pk_mul_f32 v[120:121], v[128:129], v[120:121]
	v_mov_b32_e32 v162, v163
	v_pk_fma_f32 v[124:125], v[88:89], v[84:85], v[72:73]
	v_mov_b32_e32 v134, v163
	v_mov_b32_e32 v135, v163
	v_pk_mul_f32 v[76:77], v[74:75], s[24:25] op_sel_hi:[1,0]
	v_pk_mul_f32 v[74:75], v[136:137], s[24:25] op_sel_hi:[1,0]
	v_pk_mul_f32 v[122:123], v[162:163], v[122:123]
	v_pk_fma_f32 v[136:137], v[120:121], v[82:83], v[70:71]
	v_pk_fma_f32 v[124:125], v[80:81], v[64:65], v[124:125]
	v_pk_mul_f32 v[118:119], v[134:135], v[118:119]
	v_pk_fma_f32 v[136:137], v[78:79], v[62:63], v[136:137]
	v_pk_fma_f32 v[68:69], v[74:75], v[68:69], v[124:125]
	v_pk_fma_f32 v[124:125], v[122:123], v[84:85], v[72:73]
	v_pk_fma_f32 v[66:67], v[76:77], v[66:67], v[136:137]
	v_pk_fma_f32 v[136:137], v[118:119], v[82:83], v[70:71]
	v_pk_fma_f32 v[124:125], v[88:89], v[80:81], v[124:125]
	v_pk_fma_f32 v[136:137], v[120:121], v[78:79], v[136:137]
	v_pk_fma_f32 v[124:125], v[74:75], v[64:65], v[124:125]
	v_pk_fma_f32 v[64:65], v[114:115], v[82:83], v[70:71]
	v_pk_fma_f32 v[136:137], v[76:77], v[62:63], v[136:137]
	v_pk_fma_f32 v[62:63], v[112:113], v[84:85], v[72:73]
	v_pk_fma_f32 v[64:65], v[118:119], v[78:79], v[64:65]
	v_pk_fma_f32 v[62:63], v[122:123], v[80:81], v[62:63]
	v_pk_fma_f32 v[120:121], v[120:121], v[76:77], v[64:65]
	v_pk_fma_f32 v[64:65], v[126:127], v[82:83], v[70:71]
	v_pk_fma_f32 v[88:89], v[88:89], v[74:75], v[62:63]
	v_pk_fma_f32 v[62:63], v[116:117], v[84:85], v[72:73]
	v_pk_fma_f32 v[64:65], v[114:115], v[78:79], v[64:65]
	v_pk_fma_f32 v[62:63], v[112:113], v[80:81], v[62:63]
	v_pk_fma_f32 v[114:115], v[118:119], v[76:77], v[64:65]
	v_pk_mul_f32 v[50:51], v[50:51], v[54:55]
	v_pk_mul_f32 v[64:65], v[46:47], v[54:55]
	v_pk_mul_f32 v[44:45], v[44:45], v[56:57]
	v_pk_mul_f32 v[42:43], v[42:43], v[54:55]
	v_pk_fma_f32 v[112:113], v[122:123], v[74:75], v[62:63]
	v_pk_mul_f32 v[52:53], v[52:53], v[56:57]
	v_pk_mul_f32 v[62:63], v[48:49], v[56:57]
	v_pk_mul_f32 v[46:47], v[50:51], s[26:27] op_sel_hi:[1,0]
	v_pk_mul_f32 v[50:51], v[64:65], s[26:27] op_sel_hi:[1,0]
	v_pk_mul_f32 v[54:55], v[42:43], s[26:27] op_sel_hi:[1,0]
	v_pk_mul_f32 v[56:57], v[44:45], s[26:27] op_sel_hi:[1,0]
	v_pk_mul_f32 v[64:65], v[38:39], s[26:27] op_sel_hi:[1,0]
	v_pk_mul_f32 v[38:39], v[110:111], v[176:177]
	v_pk_mul_f32 v[44:45], v[196:197], v[170:171]
	v_pk_mul_f32 v[110:111], v[128:129], v[180:181]
	v_pk_mul_f32 v[48:49], v[52:53], s[26:27] op_sel_hi:[1,0]
	v_pk_mul_f32 v[52:53], v[62:63], s[26:27] op_sel_hi:[1,0]
	v_pk_mul_f32 v[62:63], v[40:41], s[26:27] op_sel_hi:[1,0]
	v_pk_mul_f32 v[40:41], v[198:199], v[172:173]
	v_pk_mul_f32 v[42:43], v[164:165], v[174:175]
	s_waitcnt lgkmcnt(0)
	v_mov_b32_dpp v58, v44 row_shr:1 row_mask:0xf bank_mask:0xf
	v_mov_b32_dpp v59, v45 row_shr:1 row_mask:0xf bank_mask:0xf
	v_pk_mul_f32 v[86:87], v[86:87], v[184:185]
	v_pk_fma_f32 v[126:127], v[110:111], v[54:55], v[64:65]
	v_mov_b32_dpp v34, v40 row_shr:1 row_mask:0xf bank_mask:0xf
	v_mov_b32_dpp v35, v41 row_shr:1 row_mask:0xf bank_mask:0xf
	v_mov_b32_dpp v60, v42 row_shr:1 row_mask:0xf bank_mask:0xf
	v_mov_b32_dpp v61, v43 row_shr:1 row_mask:0xf bank_mask:0xf
	v_pk_mul_f32 v[118:119], v[134:135], v[178:179]
	v_pk_fma_f32 v[122:123], v[86:87], v[56:57], v[62:63]
	v_pk_fma_f32 v[126:127], v[50:51], v[58:59], v[126:127]
	v_mov_b32_dpp v36, v38 row_shr:1 row_mask:0xf bank_mask:0xf
	v_mov_b32_dpp v37, v39 row_shr:1 row_mask:0xf bank_mask:0xf
	v_pk_mul_f32 v[116:117], v[162:163], v[182:183]
	v_pk_fma_f32 v[122:123], v[52:53], v[60:61], v[122:123]
	v_pk_fma_f32 v[34:35], v[46:47], v[34:35], v[126:127]
	v_pk_fma_f32 v[126:127], v[118:119], v[54:55], v[64:65]
	v_pk_fma_f32 v[36:37], v[48:49], v[36:37], v[122:123]
	v_pk_fma_f32 v[122:123], v[116:117], v[56:57], v[62:63]
	v_pk_fma_f32 v[126:127], v[110:111], v[50:51], v[126:127]
	v_pk_fma_f32 v[44:45], v[44:45], v[54:55], v[64:65]
	v_pk_fma_f32 v[122:123], v[86:87], v[52:53], v[122:123]
	v_pk_fma_f32 v[58:59], v[46:47], v[58:59], v[126:127]
	v_pk_fma_f32 v[126:127], v[40:41], v[54:55], v[64:65]
	v_pk_fma_f32 v[42:43], v[42:43], v[56:57], v[62:63]
	v_pk_fma_f32 v[40:41], v[40:41], v[50:51], v[44:45]
	v_exp_f32_e64 v44, -v68
	v_exp_f32_e64 v45, -v69
	v_pk_fma_f32 v[60:61], v[48:49], v[60:61], v[122:123]
	v_pk_fma_f32 v[122:123], v[38:39], v[56:57], v[62:63]
	v_pk_fma_f32 v[38:39], v[38:39], v[52:53], v[42:43]
	v_exp_f32_e64 v42, -v66
	v_exp_f32_e64 v43, -v67
	v_pk_add_f32 v[44:45], v[44:45], 1.0 op_sel_hi:[1,0]
	v_pk_mul_f32 v[36:37], v[68:69], v[36:37]
	v_rcp_f32_e32 v44, v44
	v_pk_add_f32 v[42:43], v[42:43], 1.0 op_sel_hi:[1,0]
	v_rcp_f32_e32 v45, v45
	v_rcp_f32_e32 v42, v42
	v_rcp_f32_e32 v43, v43
	v_pk_mul_f32 v[34:35], v[66:67], v[34:35]
	v_pk_mul_f32 v[36:37], v[44:45], v[36:37]
	v_exp_f32_e64 v44, -v124
	v_exp_f32_e64 v45, -v125
	v_pk_mul_f32 v[34:35], v[42:43], v[34:35]
	v_exp_f32_e64 v42, -v136
	v_exp_f32_e64 v43, -v137
	v_cvt_pk_bf16_f32 v216, v34, v35
	v_cvt_pk_bf16_f32 v217, v36, v37
	global_store_dwordx4 v[94:95], v[214:217], off
	v_pk_add_f32 v[34:35], v[44:45], 1.0 op_sel_hi:[1,0]
	v_pk_add_f32 v[36:37], v[42:43], 1.0 op_sel_hi:[1,0]
	v_rcp_f32_e32 v34, v34
	v_rcp_f32_e32 v35, v35
	v_rcp_f32_e32 v36, v36
	v_rcp_f32_e32 v37, v37
	v_pk_mul_f32 v[42:43], v[124:125], v[60:61]
	v_pk_mul_f32 v[44:45], v[136:137], v[58:59]
	v_pk_mul_f32 v[34:35], v[34:35], v[42:43]
	v_exp_f32_e64 v42, -v120
	v_exp_f32_e64 v43, -v121
	v_pk_mul_f32 v[36:37], v[36:37], v[44:45]
	v_exp_f32_e64 v44, -v88
	v_exp_f32_e64 v45, -v89
	v_cvt_pk_bf16_f32 v220, v36, v37
	v_cvt_pk_bf16_f32 v221, v34, v35
	global_store_dwordx4 v[96:97], v[218:221], off
	v_pk_add_f32 v[36:37], v[42:43], 1.0 op_sel_hi:[1,0]
	v_pk_add_f32 v[34:35], v[44:45], 1.0 op_sel_hi:[1,0]
	v_rcp_f32_e32 v36, v36
	v_rcp_f32_e32 v37, v37
	v_pk_fma_f32 v[126:127], v[118:119], v[50:51], v[126:127]
	v_rcp_f32_e32 v34, v34
	v_rcp_f32_e32 v35, v35
	v_pk_fma_f32 v[122:123], v[116:117], v[52:53], v[122:123]
	v_pk_fma_f32 v[110:111], v[110:111], v[46:47], v[126:127]
	v_pk_fma_f32 v[86:87], v[86:87], v[48:49], v[122:123]
	v_pk_mul_f32 v[42:43], v[120:121], v[110:111]
	v_pk_mul_f32 v[44:45], v[88:89], v[86:87]
	v_pk_mul_f32 v[36:37], v[42:43], v[36:37]
	v_exp_f32_e64 v42, -v114
	v_exp_f32_e64 v43, -v115
	v_pk_mul_f32 v[34:35], v[44:45], v[34:35]
	v_exp_f32_e64 v44, -v112
	v_exp_f32_e64 v45, -v113
	v_cvt_pk_bf16_f32 v224, v36, v37
	v_cvt_pk_bf16_f32 v225, v34, v35
	global_store_dwordx4 v[100:101], v[222:225], off
	v_pk_add_f32 v[36:37], v[42:43], 1.0 op_sel_hi:[1,0]
	v_pk_add_f32 v[34:35], v[44:45], 1.0 op_sel_hi:[1,0]
	v_rcp_f32_e32 v36, v36
	v_rcp_f32_e32 v37, v37
	v_rcp_f32_e32 v34, v34
	v_rcp_f32_e32 v35, v35
	v_pk_fma_f32 v[40:41], v[118:119], v[46:47], v[40:41]
	v_pk_fma_f32 v[38:39], v[116:117], v[48:49], v[38:39]
	v_pk_mul_f32 v[40:41], v[114:115], v[40:41]
	v_pk_mul_f32 v[38:39], v[112:113], v[38:39]
	v_pk_mul_f32 v[36:37], v[40:41], v[36:37]
	v_pk_mul_f32 v[34:35], v[38:39], v[34:35]
	v_cvt_pk_bf16_f32 v228, v36, v37
	v_mov_b32_e32 v38, 0
	v_cvt_pk_bf16_f32 v229, v34, v35
	global_store_dwordx4 v[104:105], v[226:229], off
	v_mov_b32_e32 v34, 0
	v_mov_b32_e32 v39, 0
	v_mov_b32_e32 v40, 0
	v_mov_b32_e32 v41, 0
	v_mov_b32_e32 v42, 0
	v_mov_b32_e32 v43, 0
	v_mov_b32_e32 v44, 0
	v_mov_b32_e32 v45, 0
	s_and_saveexec_b64 s[4:5], vcc
	s_cbranch_execz .LBB0_2106
	ds_read_b128 v[38:41], v186 offset:128
	ds_read_b128 v[42:45], v186 offset:144

.LBB0_2108:
	s_or_b64 exec, exec, s[4:5]
	v_cvt_f32_i32_e32 v23, v23
	v_cvt_f32_i32_e32 v22, v22
	v_cvt_f32_i32_e32 v25, v25
	v_cvt_f32_i32_e32 v24, v24
	v_cvt_f32_i32_e32 v21, v21
	v_cvt_f32_i32_e32 v20, v20
	v_mov_b32_e32 v86, v131
	v_mov_b32_e32 v87, v131
	v_cvt_f32_i32_e32 v17, v17
	v_cvt_f32_i32_e32 v16, v16
	v_cvt_f32_i32_e32 v5, v5
	v_cvt_f32_i32_e32 v4, v4
	v_mov_b32_e32 v88, v131
	v_mov_b32_e32 v89, v131
	v_pk_mul_f32 v[94:95], v[86:87], v[22:23]
	v_pk_fma_f32 v[22:23], v[60:61], v[84:85], v[72:73]
	v_cvt_f32_i32_e32 v15, v15
	v_cvt_f32_i32_e32 v14, v14
	v_cvt_f32_i32_e32 v9, v9
	v_cvt_f32_i32_e32 v8, v8
	v_cvt_f32_i32_e32 v3, v3
	v_cvt_f32_i32_e32 v2, v2
	v_pk_mul_f32 v[24:25], v[88:89], v[24:25]
	v_pk_fma_f32 v[60:61], v[66:67], v[82:83], v[70:71]
	v_pk_fma_f32 v[22:23], v[32:33], v[80:81], v[22:23]
	v_cvt_f32_i32_e32 v67, v19
	v_cvt_f32_i32_e32 v66, v18
	v_mov_b32_e32 v131, v130
	v_pk_fma_f32 v[32:33], v[32:33], v[84:85], v[72:73]
	v_cvt_f32_i32_e32 v13, v13
	v_cvt_f32_i32_e32 v12, v12
	v_cvt_f32_i32_e32 v7, v7
	v_cvt_f32_i32_e32 v6, v6
	v_pk_fma_f32 v[22:23], v[24:25], v[74:75], v[22:23]
	v_pk_mul_f32 v[20:21], v[130:131], v[20:21]
	v_pk_fma_f32 v[32:33], v[24:25], v[80:81], v[32:33]
	v_pk_fma_f32 v[24:25], v[24:25], v[84:85], v[72:73]
	v_cvt_f32_i32_e32 v11, v11
	v_cvt_f32_i32_e32 v10, v10
	v_mov_b32_e32 v68, v130
	v_mov_b32_e32 v69, v130
	v_pk_fma_f32 v[32:33], v[20:21], v[74:75], v[32:33]
	v_pk_fma_f32 v[24:25], v[20:21], v[80:81], v[24:25]
	v_pk_fma_f32 v[20:21], v[20:21], v[84:85], v[72:73]
	v_pk_mul_f32 v[4:5], v[132:133], v[4:5]
	v_pk_mul_f32 v[16:17], v[130:131], v[16:17]
	v_pk_fma_f32 v[60:61], v[58:59], v[78:79], v[60:61]
	v_pk_fma_f32 v[58:59], v[58:59], v[82:83], v[70:71]
	v_pk_fma_f32 v[20:21], v[80:81], v[44:45], v[20:21]
	v_pk_mul_f32 v[8:9], v[30:31], v[8:9]
	v_pk_mul_f32 v[2:3], v[90:91], v[2:3]
	s_waitcnt lgkmcnt(0)
	v_mov_b32_dpp v28, v4 row_shr:1 row_mask:0xf bank_mask:0xf
	v_mov_b32_dpp v29, v5 row_shr:1 row_mask:0xf bank_mask:0xf
	v_pk_mul_f32 v[14:15], v[68:69], v[14:15]
	v_pk_fma_f32 v[30:31], v[16:17], v[56:57], v[62:63]
	v_pk_fma_f32 v[18:19], v[94:95], v[76:77], v[60:61]
	v_pk_mul_f32 v[60:61], v[68:69], v[66:67]
	v_pk_fma_f32 v[58:59], v[94:95], v[78:79], v[58:59]
	v_pk_fma_f32 v[66:67], v[94:95], v[82:83], v[70:71]
	v_pk_fma_f32 v[20:21], v[74:75], v[40:41], v[20:21]
	v_pk_mul_f32 v[6:7], v[92:93], v[6:7]
	v_mov_b32_dpp v26, v2 row_shr:1 row_mask:0xf bank_mask:0xf
	v_mov_b32_dpp v27, v3 row_shr:1 row_mask:0xf bank_mask:0xf
	v_mov_b32_dpp v36, v8 row_shr:1 row_mask:0xf bank_mask:0xf
	v_mov_b32_dpp v37, v9 row_shr:1 row_mask:0xf bank_mask:0xf
	v_pk_mul_f32 v[12:13], v[88:89], v[12:13]
	v_pk_fma_f32 v[40:41], v[14:15], v[54:55], v[64:65]
	v_pk_fma_f32 v[30:31], v[52:53], v[28:29], v[30:31]
	v_pk_fma_f32 v[58:59], v[60:61], v[76:77], v[58:59]
	v_pk_fma_f32 v[66:67], v[60:61], v[78:79], v[66:67]
	v_pk_fma_f32 v[60:61], v[60:61], v[82:83], v[70:71]
	v_mov_b32_dpp v34, v6 row_shr:1 row_mask:0xf bank_mask:0xf
	v_mov_b32_dpp v35, v7 row_shr:1 row_mask:0xf bank_mask:0xf
	v_pk_mul_f32 v[10:11], v[86:87], v[10:11]
	v_pk_fma_f32 v[40:41], v[50:51], v[26:27], v[40:41]
	v_pk_fma_f32 v[30:31], v[48:49], v[36:37], v[30:31]
	v_pk_fma_f32 v[36:37], v[12:13], v[56:57], v[62:63]
	v_pk_fma_f32 v[66:67], v[76:77], v[42:43], v[66:67]
	v_pk_fma_f32 v[42:43], v[78:79], v[42:43], v[60:61]
	v_pk_fma_f32 v[34:35], v[46:47], v[34:35], v[40:41]
	v_pk_fma_f32 v[40:41], v[10:11], v[54:55], v[64:65]
	v_pk_fma_f32 v[36:37], v[16:17], v[52:53], v[36:37]
	v_pk_fma_f32 v[4:5], v[4:5], v[56:57], v[62:63]
	v_pk_fma_f32 v[38:39], v[76:77], v[38:39], v[42:43]
	v_pk_fma_f32 v[40:41], v[14:15], v[50:51], v[40:41]
	v_pk_fma_f32 v[28:29], v[48:49], v[28:29], v[36:37]
	v_pk_fma_f32 v[36:37], v[8:9], v[56:57], v[62:63]
	v_pk_fma_f32 v[2:3], v[2:3], v[54:55], v[64:65]
	v_pk_fma_f32 v[4:5], v[8:9], v[52:53], v[4:5]
	v_exp_f32_e64 v8, -v20
	v_exp_f32_e64 v9, -v21
	v_pk_fma_f32 v[26:27], v[46:47], v[26:27], v[40:41]
	v_pk_fma_f32 v[40:41], v[6:7], v[54:55], v[64:65]
	v_pk_fma_f32 v[2:3], v[6:7], v[50:51], v[2:3]
	v_exp_f32_e64 v6, -v38
	v_exp_f32_e64 v7, -v39
	v_pk_add_f32 v[8:9], v[8:9], 1.0 op_sel_hi:[1,0]
	v_pk_fma_f32 v[40:41], v[10:11], v[50:51], v[40:41]
	v_rcp_f32_e32 v8, v8
	v_pk_add_f32 v[6:7], v[6:7], 1.0 op_sel_hi:[1,0]
	v_rcp_f32_e32 v9, v9
	v_rcp_f32_e32 v6, v6
	v_rcp_f32_e32 v7, v7
	v_pk_fma_f32 v[2:3], v[10:11], v[46:47], v[2:3]
	v_pk_mul_f32 v[10:11], v[20:21], v[30:31]
	v_pk_fma_f32 v[24:25], v[74:75], v[44:45], v[24:25]
	v_pk_fma_f32 v[36:37], v[12:13], v[52:53], v[36:37]
	v_pk_fma_f32 v[4:5], v[12:13], v[48:49], v[4:5]
	v_pk_mul_f32 v[12:13], v[38:39], v[34:35]
	v_pk_mul_f32 v[8:9], v[8:9], v[10:11]
	v_exp_f32_e64 v10, -v66
	v_exp_f32_e64 v11, -v67
	v_pk_mul_f32 v[6:7], v[6:7], v[12:13]
	v_exp_f32_e64 v12, -v24
	v_exp_f32_e64 v13, -v25
	v_cvt_pk_bf16_f32 v244, v6, v7
	v_cvt_pk_bf16_f32 v245, v8, v9
	v_pk_add_f32 v[8:9], v[10:11], 1.0 op_sel_hi:[1,0]
	global_store_dwordx4 v[98:99], v[242:245], off
	v_pk_add_f32 v[6:7], v[12:13], 1.0 op_sel_hi:[1,0]
	v_rcp_f32_e32 v8, v8
	v_rcp_f32_e32 v9, v9
	v_rcp_f32_e32 v6, v6
	v_rcp_f32_e32 v7, v7
	v_pk_mul_f32 v[12:13], v[66:67], v[26:27]
	v_pk_mul_f32 v[10:11], v[24:25], v[28:29]
	v_pk_mul_f32 v[8:9], v[8:9], v[12:13]
	v_exp_f32_e64 v12, -v32
	v_exp_f32_e64 v13, -v33
	v_pk_mul_f32 v[6:7], v[6:7], v[10:11]
	v_exp_f32_e64 v10, -v58
	v_exp_f32_e64 v11, -v59
	v_cvt_pk_bf16_f32 v248, v8, v9
	v_cvt_pk_bf16_f32 v249, v6, v7
	v_pk_add_f32 v[6:7], v[12:13], 1.0 op_sel_hi:[1,0]
	global_store_dwordx4 v[102:103], v[246:249], off
	v_pk_add_f32 v[8:9], v[10:11], 1.0 op_sel_hi:[1,0]
	v_rcp_f32_e32 v6, v6
	v_rcp_f32_e32 v7, v7
	v_rcp_f32_e32 v8, v8
	v_rcp_f32_e32 v9, v9
	v_pk_fma_f32 v[16:17], v[16:17], v[48:49], v[36:37]
	v_pk_fma_f32 v[14:15], v[14:15], v[46:47], v[40:41]
	v_pk_mul_f32 v[10:11], v[32:33], v[16:17]
	v_pk_mul_f32 v[12:13], v[58:59], v[14:15]
	v_pk_mul_f32 v[6:7], v[10:11], v[6:7]
	v_exp_f32_e64 v10, -v18
	v_exp_f32_e64 v11, -v19
	v_pk_mul_f32 v[8:9], v[12:13], v[8:9]
	v_exp_f32_e64 v12, -v22
	v_exp_f32_e64 v13, -v23
	v_cvt_pk_bf16_f32 v252, v8, v9
	v_cvt_pk_bf16_f32 v253, v6, v7
	global_store_dwordx4 v[106:107], v[250:253], off
	v_pk_add_f32 v[8:9], v[10:11], 1.0 op_sel_hi:[1,0]
	v_pk_add_f32 v[6:7], v[12:13], 1.0 op_sel_hi:[1,0]
	v_rcp_f32_e32 v8, v8
	v_rcp_f32_e32 v9, v9
	v_rcp_f32_e32 v6, v6
	v_rcp_f32_e32 v7, v7
	v_pk_mul_f32 v[2:3], v[18:19], v[2:3]
	v_pk_mul_f32 v[4:5], v[22:23], v[4:5]
	v_pk_mul_f32 v[2:3], v[2:3], v[8:9]
	v_pk_mul_f32 v[4:5], v[4:5], v[6:7]
	v_cvt_pk_bf16_f32 v2, v2, v3
	s_andn2_b64 vcc, exec, s[0:1]
	v_cvt_pk_bf16_f32 v3, v4, v5
	global_store_dwordx2 v[108:109], v[2:3], off offset:8
	s_mov_b64 s[0:1], -1
	s_cbranch_vccnz .LBB0_2052
	s_and_b32 s0, s85, 1
	v_lshl_add_u32 v2, s28, 7, v1
	s_mul_i32 s1, s0, 0x1400
	v_ashrrev_i32_e32 v3, 31, v2
	s_add_i32 s1, s25, s1
	v_lshlrev_b64 v[2:3], 2, v[2:3]
	v_lshl_add_u64 v[4:5], v[138:139], 0, v[2:3]
	s_mov_b32 m0, s1
	v_lshl_add_u64 v[2:3], v[140:141], 0, v[2:3]
	global_load_lds_dword v[4:5], off
	s_add_i32 m0, s1, 0x800
	s_andn2_b64 vcc, exec, s[8:9]
	global_load_lds_dword v[2:3], off
	s_cbranch_vccnz .LBB0_2111
	s_lshl_b32 s4, s28, 8
	s_ashr_i32 s5, s4, 31
	v_lshl_add_u64 v[2:3], s[4:5], 2, v[150:151]
	s_add_i32 m0, s1, 0x1000
	s_nop 0
	global_load_lds_dword v[2:3], off
